# nt also on the row / gate loads of P5, the P6 epilogue and the P7 / P11 row epilogues (last use of that data)
# speedup vs baseline: 1.0362x; 1.0018x over previous
; __global__ void __launch_bounds__(NTHR, 2) fwd_kernel(Args a) {
;     ...
;       for (int task = gw; task < NB * 1023; task += NGW) { const int b = task / 1023, row = 1 + task % 1023;
;           const bf16_t* src = Ff + (size_t)(b * SEQ + row) * FNW; bf16_t* dst = Ff + (size_t)(b * SEQ + SEQ - row) * FNW;
; #pragma unroll
;           for (int g = 0; g < 4; ++g) { const bf16_t* sg = src + g * 256; const int c = 4 * lane;
;               const unsigned e0 = sg[(256 - c) & 255], e1 = sg[255 - c], e2 = sg[254 - c], e3 = sg[253 - c];
;               u32x2 w; w.x = e0 | (e1 << 16); w.y = e2 | (e3 << 16); *(u32x2*)(dst + g * 256 + c) = w; } }
.LBB0_1337:
	s_mul_hi_i32 s6, s5, 0x80200803
	s_add_i32 s6, s6, s5
	s_lshr_b32 s7, s6, 31
	s_ashr_i32 s6, s6, 9
	s_add_i32 s8, s6, s7
	s_mul_i32 s6, s8, 0x401
	s_add_i32 s6, s5, s6
	s_add_i32 s6, s6, 1
	s_ashr_i32 s7, s6, 31
	s_lshl_b64 s[6:7], s[6:7], 11
	s_add_u32 s6, s78, s6
	s_addc_u32 s7, s79, s7
	v_lshl_add_u64 v[8:9], v[4:5], 1, s[6:7]
	global_load_ushort v16, v1, s[6:7] nt
	global_load_dword v17, v6, s[6:7] nt
	global_load_ushort v24, v[8:9], off offset:6 nt
	global_load_ushort v18, v1, s[6:7] offset:512 nt
	global_load_dword v19, v6, s[6:7] offset:512 nt
	global_load_ushort v25, v[8:9], off offset:518 nt
	global_load_ushort v20, v1, s[6:7] offset:1024 nt
	global_load_dword v21, v6, s[6:7] offset:1024 nt
	global_load_ushort v26, v[8:9], off offset:1030 nt
	global_load_ushort v22, v1, s[6:7] offset:1536 nt
	global_load_dword v23, v6, s[6:7] offset:1536 nt
	global_load_ushort v27, v[8:9], off offset:1542 nt
	s_mulk_i32 s8, 0xbff
	s_add_i32 s8, s3, s8
	s_ashr_i32 s9, s8, 31
	s_lshl_b64 s[8:9], s[8:9], 11
	v_lshl_add_u64 v[10:11], v[2:3], 0, s[8:9]
	s_add_i32 s5, s5, s10
	s_sub_i32 s3, s3, s10
	s_cmpk_gt_i32 s5, 0xffb
	s_waitcnt vmcnt(9)
	v_lshl_or_b32 v16, v24, 16, v16
	v_alignbit_b32 v17, v17, v17, 16
	global_store_dwordx2 v[10:11], v[16:17], off
	s_waitcnt vmcnt(7)
	v_lshl_or_b32 v18, v25, 16, v18
	v_alignbit_b32 v19, v19, v19, 16
	global_store_dwordx2 v[10:11], v[18:19], off offset:512
	s_waitcnt vmcnt(5)
	v_lshl_or_b32 v20, v26, 16, v20
	v_alignbit_b32 v21, v21, v21, 16
	global_store_dwordx2 v[10:11], v[20:21], off offset:1024
	s_waitcnt vmcnt(3)
	v_lshl_or_b32 v22, v27, 16, v22
	v_alignbit_b32 v23, v23, v23, 16
	global_store_dwordx2 v[10:11], v[22:23], off offset:1536
	s_cbranch_scc0 .LBB0_1337

; __device__ __forceinline__ float bf2f(unsigned short h) { return __uint_as_float((unsigned)h << 16); }
; __device__ __forceinline__ unsigned f2bfhw(float f) { return (unsigned)__builtin_bit_cast(unsigned short, (__bf16)f); }
; __device__ __forceinline__ f32x4 ld_bf4(const bf16_t* p) { u32x2 w = *(const u32x2*)p; return (f32x4){__uint_as_float(w.x << 16), __uint_as_float(w.x & 0xffff0000u), __uint_as_float(w.y << 16), __uint_as_float(w.y & 0xffff0000u)}; }
; __global__ void __launch_bounds__(NTHR, 2) fwd_kernel(Args a) {
;     ...
;       for (int task = gw; task < 16 * 256; task += NGW) { const int bz = task >> 8, ch = task & 255;
;           const bf16_t* xp = XT + (size_t)bz * 256 * 4096 + (size_t)ch * 4096; float sacc = 0.f;
; #pragma unroll
;           for (int it = 0; it < 4; ++it) { const bf16x8 xv = *(const bf16x8*)(xp + it * 512 + lane * 8);
; #pragma unroll
;               for (int e = 0; e < 8; e += 2) sacc += bf2f((unsigned short)xv[e]) - bf2f((unsigned short)xv[e + 1]); }
;           sacc = wave_sum(sacc);
;           if (lane == 0) Ff[(size_t)((bz >> 2) * SEQ + 1024) * FNW + (bz & 3) * 256 + ch] = (bf16_t)f2bfhw(sacc * 0.02209708691207961f); } }
;     ...
;     for (int it = 0; it < (G == 256 ? 1 : 0); ++it) { const int lt = (bx >> 3) * 8 + wave, bhx = 2 * (bx & 7) + (lt >> 7), h = bhx & 3, b = bhx >> 2, n = (lt >> 2) & 31, ct = lt & 3, fr = lane & 15, fq = lane >> 4;
;         f32x4 ov[16]; float ss = 0.f;
; #pragma unroll
;         for (int t = 0; t < 16; ++t) { const size_t o = ((((((size_t)(b * 32 + n) * 4 + h) * 8 + (t >> 1)) * 4 + ct) * 2 + (t & 1)) * 64 + lane) << 2;
;             const f32x4 x = ld_bf4(Of + o) + ld_bf4(Ob + o); ov[t] = x; ss += (x[0] * x[0] + x[1] * x[1]) + (x[2] * x[2] + x[3] * x[3]); }
.LBB0_1341:
	s_ashr_i32 s2, s4, 8
	s_ashr_i32 s3, s2, 31
	s_and_b32 s7, s4, 0xff
	s_lshl_b64 s[2:3], s[2:3], 21
	s_add_u32 s2, s90, s2
	s_addc_u32 s3, s91, s3
	s_lshl_b32 s8, s7, 13
	s_add_u32 s2, s2, s8
	s_addc_u32 s3, s3, 0
	s_waitcnt lgkmcnt(0)
	global_load_dwordx4 v[8:11], v0, s[2:3] nt
	global_load_dwordx4 v[12:15], v0, s[2:3] offset:1024 nt
	global_load_dwordx4 v[16:19], v0, s[2:3] offset:2048 nt
	global_load_dwordx4 v[20:23], v0, s[2:3] offset:3072 nt
	s_waitcnt vmcnt(3)
	v_lshlrev_b32_e32 v7, 16, v8
	v_and_b32_e32 v8, 0xffff0000, v8
	v_lshlrev_b32_e32 v24, 16, v9
	v_and_b32_e32 v9, 0xffff0000, v9
	v_sub_f32_e32 v7, v7, v8
	v_lshlrev_b32_e32 v25, 16, v10
	v_and_b32_e32 v10, 0xffff0000, v10
	v_sub_f32_e32 v8, v24, v9
	v_add_f32_e32 v7, 0, v7
	v_lshlrev_b32_e32 v26, 16, v11
	v_and_b32_e32 v11, 0xffff0000, v11
	v_sub_f32_e32 v9, v25, v10
	v_add_f32_e32 v7, v7, v8
	s_waitcnt vmcnt(2)
	v_lshlrev_b32_e32 v27, 16, v12
	v_and_b32_e32 v12, 0xffff0000, v12
	v_sub_f32_e32 v10, v26, v11
	v_add_f32_e32 v7, v7, v9
	v_lshlrev_b32_e32 v28, 16, v13
	v_and_b32_e32 v13, 0xffff0000, v13
	v_sub_f32_e32 v11, v27, v12
	v_add_f32_e32 v7, v7, v10
	v_lshlrev_b32_e32 v29, 16, v14
	v_and_b32_e32 v14, 0xffff0000, v14
	v_sub_f32_e32 v12, v28, v13
	v_add_f32_e32 v7, v7, v11
	v_lshlrev_b32_e32 v30, 16, v15
	v_and_b32_e32 v15, 0xffff0000, v15
	v_sub_f32_e32 v13, v29, v14
	v_add_f32_e32 v7, v7, v12
	s_waitcnt vmcnt(1)
	v_lshlrev_b32_e32 v31, 16, v16
	v_and_b32_e32 v16, 0xffff0000, v16
	v_sub_f32_e32 v14, v30, v15
	v_add_f32_e32 v7, v7, v13
	v_lshlrev_b32_e32 v32, 16, v17
	v_and_b32_e32 v17, 0xffff0000, v17
	v_sub_f32_e32 v15, v31, v16
	v_add_f32_e32 v7, v7, v14
	v_lshlrev_b32_e32 v33, 16, v18
	v_and_b32_e32 v18, 0xffff0000, v18
	v_sub_f32_e32 v16, v32, v17
	v_add_f32_e32 v7, v7, v15
	v_lshlrev_b32_e32 v34, 16, v19
	v_and_b32_e32 v19, 0xffff0000, v19
	v_sub_f32_e32 v17, v33, v18
	v_add_f32_e32 v7, v7, v16
	s_waitcnt vmcnt(0)
	v_lshlrev_b32_e32 v35, 16, v20
	v_and_b32_e32 v20, 0xffff0000, v20
	v_sub_f32_e32 v18, v34, v19
	v_add_f32_e32 v7, v7, v17
	v_lshlrev_b32_e32 v36, 16, v21
	v_and_b32_e32 v21, 0xffff0000, v21
	v_sub_f32_e32 v19, v35, v20
	v_add_f32_e32 v7, v7, v18
	v_lshlrev_b32_e32 v37, 16, v22
	v_and_b32_e32 v22, 0xffff0000, v22
	v_sub_f32_e32 v20, v36, v21
	v_add_f32_e32 v7, v7, v19
	v_lshlrev_b32_e32 v38, 16, v23
	v_and_b32_e32 v23, 0xffff0000, v23
	v_sub_f32_e32 v21, v37, v22
	v_add_f32_e32 v7, v7, v20
	v_add_f32_e32 v7, v7, v21
	v_sub_f32_e32 v8, v38, v23
	v_add_f32_e32 v7, v7, v8
	ds_bpermute_b32 v8, v1, v7
	s_waitcnt lgkmcnt(0)
	v_add_f32_e32 v7, v7, v8
	ds_bpermute_b32 v8, v2, v7
	s_waitcnt lgkmcnt(0)
	v_add_f32_e32 v7, v7, v8
	ds_bpermute_b32 v8, v3, v7
	s_waitcnt lgkmcnt(0)
	v_add_f32_e32 v7, v7, v8
	ds_bpermute_b32 v8, v4, v7
	s_waitcnt lgkmcnt(0)
	v_add_f32_e32 v7, v7, v8
	ds_bpermute_b32 v8, v5, v7
	s_waitcnt lgkmcnt(0)
	v_add_f32_e32 v7, v7, v8
	ds_bpermute_b32 v8, v6, v7
	s_and_saveexec_b64 s[2:3], vcc
	s_cbranch_execz .LBB0_1340
	s_and_b32 s8, s5, 0xfffff800
	s_bitset1_b32 s8, 10
	s_ashr_i32 s9, s8, 31
	s_and_b32 s10, s4, 0x300
	s_lshl_b64 s[8:9], s[8:9], 11
	s_add_u32 s8, s78, s8
	s_addc_u32 s9, s79, s9
	s_lshl_b32 s10, s10, 1
	s_waitcnt lgkmcnt(0)
	v_add_f32_e32 v7, v7, v8
	s_add_u32 s8, s8, s10
	v_mul_f32_e32 v7, 0x3cb504f3, v7
	s_addc_u32 s9, s9, 0
	s_lshl_b32 s7, s7, 1
	v_cvt_pk_bf16_f32 v7, v7, s0
	v_mov_b32_e32 v8, s7
	global_store_short v8, v7, s[8:9]
	s_branch .LBB0_1340
.LBB0_1343:
	v_readlane_b32 s2, v254, 54
	v_mov_b32_e32 v0, v189
	v_readlane_b32 s3, v254, 55
	s_andn2_b64 vcc, exec, s[2:3]
	v_readfirstlane_b32 s2, v0
	s_cbranch_vccnz .LBB0_1345
	s_ashr_i32 s2, s2, 6
	s_and_b32 s3, s88, -8
	s_add_i32 s3, s2, s3
	s_lshl_b32 s4, s33, 1
	s_ashr_i32 s5, s3, 7
	s_add_i32 s5, s5, s4
	s_ashr_i32 s7, s5, 2
	s_bfe_u32 s3, s3, 0x50002
	s_and_b32 s8, s2, 3
	s_lshl_b32 s2, s7, 5
	s_or_b32 s4, s2, s3
	s_lshl_b32 s2, s7, 11
	s_lshl_b32 s3, s3, 6
	v_readlane_b32 s12, v254, 17
	s_and_b32 s6, s5, 3
	s_or_b32 s2, s2, s3
	s_lshl_b32 s3, s8, 4
	v_readlane_b32 s13, v254, 18
	v_readlane_b32 s20, v254, 25
	v_readlane_b32 s21, v254, 26
	s_ashr_i32 s5, s4, 31
	s_or_b32 s7, s2, s3
	s_lshl_b32 s9, s6, 8
	s_lshl_b32 s2, s6, 10
	s_mov_b64 s[12:13], s[20:21]
	s_add_u32 s2, s12, s2
	s_addc_u32 s3, s13, 0
	s_lshl_b64 s[4:5], s[4:5], 17
	s_lshl_b32 s6, s6, 15
	s_or_b32 s4, s4, s6
	s_lshl_b32 s6, s8, 10
	v_lshlrev_b32_e32 v1, 3, v0
	s_or_b32 s4, s4, s6
	v_and_b32_e32 v1, 0x1f8, v1
	s_waitcnt vmcnt(18)
	v_or_b32_e32 v22, s4, v1
	v_mov_b32_e32 v23, s5
	v_lshl_add_u64 v[2:3], s[82:83], 0, v[22:23]
	v_lshl_add_u64 v[4:5], s[80:81], 0, v[22:23]
	global_load_dwordx2 v[2:3], v[2:3], off nt
	v_or_b32_e32 v6, 0x200, v22
	global_load_dwordx2 v[4:5], v[4:5], off nt
	v_mov_b32_e32 v7, s5
	s_waitcnt vmcnt(17) lgkmcnt(0)
	v_lshl_add_u64 v[8:9], s[82:83], 0, v[6:7]
	v_lshl_add_u64 v[6:7], s[80:81], 0, v[6:7]
	global_load_dwordx2 v[8:9], v[8:9], off nt
	v_mov_b32_e32 v11, s5
	global_load_dwordx2 v[6:7], v[6:7], off nt
	v_or_b32_e32 v10, 0x1000, v22
	v_mov_b32_e32 v15, s5
	v_or_b32_e32 v14, 0x1200, v22
	v_lshl_add_u64 v[12:13], s[82:83], 0, v[10:11]
	v_lshl_add_u64 v[10:11], s[80:81], 0, v[10:11]
	v_lshl_add_u64 v[16:17], s[82:83], 0, v[14:15]
	v_lshl_add_u64 v[14:15], s[80:81], 0, v[14:15]
	global_load_dwordx2 v[12:13], v[12:13], off nt
	v_mbcnt_lo_u32_b32 v1, -1, 0
	global_load_dwordx2 v[16:17], v[16:17], off nt
	s_waitcnt vmcnt(8)
; __device__ __forceinline__ f32x4 ld_bf4(const bf16_t* p) { u32x2 w = *(const u32x2*)p; return (f32x4){__uint_as_float(w.x << 16), __uint_as_float(w.x & 0xffff0000u), __uint_as_float(w.y << 16), __uint_as_float(w.y & 0xffff0000u)}; }
; __global__ void __launch_bounds__(NTHR, 2) fwd_kernel(Args a) {
;     ...
;     for (int it = 0; it < (G == 256 ? 1 : 0); ++it) { const int lt = (bx >> 3) * 8 + wave, bhx = 2 * (bx & 7) + (lt >> 7), h = bhx & 3, b = bhx >> 2, n = (lt >> 2) & 31, ct = lt & 3, fr = lane & 15, fq = lane >> 4;
;         f32x4 ov[16]; float ss = 0.f;
; #pragma unroll
;         for (int t = 0; t < 16; ++t) { const size_t o = ((((((size_t)(b * 32 + n) * 4 + h) * 8 + (t >> 1)) * 4 + ct) * 2 + (t & 1)) * 64 + lane) << 2;
;             const f32x4 x = ld_bf4(Of + o) + ld_bf4(Ob + o); ov[t] = x; ss += (x[0] * x[0] + x[1] * x[1]) + (x[2] * x[2] + x[3] * x[3]); }
;         ss += __shfl_xor(ss, 16); ss += __shfl_xor(ss, 32);
;         const float rstd = rsqrtf(ss * (1.0f / DV) + EPS);
;         const size_t ro = (size_t)(b * SEQ + n * 64 + 16 * ct + fr) * VW + h * DV + 4 * fq;
	v_mbcnt_hi_u32_b32 v68, -1, v1
	global_load_dwordx2 v[14:15], v[14:15], off nt
	v_and_b32_e32 v19, 64, v68
	global_load_dwordx2 v[10:11], v[10:11], off nt
	v_xor_b32_e32 v18, 16, v68
	v_add_u32_e32 v70, 64, v19
	v_lshrrev_b32_e32 v1, 2, v0
	v_cmp_lt_i32_e32 vcc, v18, v70
	v_and_b32_e32 v20, 12, v1
	v_mov_b32_e32 v19, s5
	v_cndmask_b32_e32 v1, v68, v18, vcc
	v_or_b32_e32 v18, 0x2000, v22
	v_lshl_add_u64 v[26:27], s[82:83], 0, v[18:19]
	v_lshl_add_u64 v[18:19], s[80:81], 0, v[18:19]
	global_load_dwordx2 v[26:27], v[26:27], off nt
	s_nop 0
	global_load_dwordx2 v[30:31], v[18:19], off nt
	v_and_or_b32 v0, v0, 15, s7
	v_lshlrev_b32_e32 v71, 2, v1
	v_ashrrev_i32_e32 v1, 31, v0
	v_lshlrev_b64 v[0:1], 10, v[0:1]
	v_or3_b32 v0, v0, s9, v20
	v_mov_b32_e32 v21, s5
	v_readlane_b32 s4, v254, 42
	v_lshlrev_b32_e32 v69, 2, v20
	v_lshlrev_b64 v[24:25], 1, v[0:1]
	v_readlane_b32 s5, v254, 43
	v_or_b32_e32 v20, 0x2200, v22
	v_lshl_add_u64 v[28:29], s[82:83], 0, v[20:21]
	v_lshl_add_u64 v[0:1], s[4:5], 0, v[24:25]
	global_load_dwordx2 v[28:29], v[28:29], off nt
	s_mov_b32 s4, 0x800000
	v_lshl_add_u64 v[24:25], s[0:1], 0, v[24:25]
	v_readlane_b32 s14, v254, 19
	v_readlane_b32 s15, v254, 20
	v_readlane_b32 s16, v254, 21
	v_readlane_b32 s17, v254, 22
	v_readlane_b32 s18, v254, 23
	v_readlane_b32 s19, v254, 24
	v_readlane_b32 s22, v254, 27
	v_readlane_b32 s23, v254, 28
	v_readlane_b32 s24, v254, 29
	v_readlane_b32 s25, v254, 30
	v_readlane_b32 s26, v254, 31
	v_readlane_b32 s27, v254, 32
	global_load_dwordx2 v[86:87], v[0:1], off nt
	s_waitcnt vmcnt(11)
	v_lshlrev_b32_e32 v18, 16, v2
	v_and_b32_e32 v19, 0xffff0000, v2
	v_lshlrev_b32_e32 v32, 16, v3
	v_and_b32_e32 v33, 0xffff0000, v3
	s_waitcnt vmcnt(10)
	v_lshlrev_b32_e32 v2, 16, v4
	v_and_b32_e32 v3, 0xffff0000, v4
	v_lshlrev_b32_e32 v4, 16, v5
	v_and_b32_e32 v5, 0xffff0000, v5
	v_pk_add_f32 v[2:3], v[18:19], v[2:3]
	v_pk_add_f32 v[4:5], v[32:33], v[4:5]
	v_pk_mul_f32 v[36:37], v[2:3], v[2:3]
	v_pk_mul_f32 v[34:35], v[4:5], v[4:5]
	s_waitcnt vmcnt(9)
	v_lshlrev_b32_e32 v18, 16, v8
	v_pk_mov_b32 v[38:39], v[36:37], v[34:35] op_sel:[1,0]
	v_mov_b32_e32 v37, v35
	v_and_b32_e32 v19, 0xffff0000, v8
	v_lshlrev_b32_e32 v8, 16, v9
	v_and_b32_e32 v9, 0xffff0000, v9
	s_waitcnt vmcnt(8)
	v_lshlrev_b32_e32 v32, 16, v6
	v_and_b32_e32 v33, 0xffff0000, v6
	v_pk_add_f32 v[34:35], v[38:39], v[36:37]
	v_lshlrev_b32_e32 v36, 16, v7
	v_and_b32_e32 v37, 0xffff0000, v7
	v_pk_add_f32 v[6:7], v[18:19], v[32:33]
	v_pk_add_f32 v[8:9], v[8:9], v[36:37]
	v_pk_mul_f32 v[32:33], v[6:7], v[6:7]
	v_pk_mul_f32 v[18:19], v[8:9], v[8:9]
	s_waitcnt vmcnt(4)
	v_lshlrev_b32_e32 v40, 16, v10
	v_pk_mov_b32 v[36:37], v[32:33], v[18:19] op_sel:[1,0]
	v_mov_b32_e32 v33, v19
	v_lshl_add_u64 v[18:19], s[80:81], 0, v[20:21]
	global_load_dwordx2 v[38:39], v[18:19], off nt
	v_or_b32_e32 v18, 0x3000, v22
	v_mov_b32_e32 v19, v23
	v_pk_add_f32 v[32:33], v[36:37], v[32:33]
	v_lshl_add_u64 v[36:37], s[82:83], 0, v[18:19]
	v_lshl_add_u64 v[18:19], s[80:81], 0, v[18:19]
	global_load_dwordx2 v[36:37], v[36:37], off nt
	v_lshlrev_b32_e32 v20, 16, v12
	global_load_dwordx2 v[42:43], v[18:19], off nt
	v_and_b32_e32 v21, 0xffff0000, v12
	v_lshlrev_b32_e32 v12, 16, v13
	v_and_b32_e32 v13, 0xffff0000, v13
	v_and_b32_e32 v41, 0xffff0000, v10
	v_lshlrev_b32_e32 v10, 16, v11
	v_and_b32_e32 v11, 0xffff0000, v11
	v_pk_add_f32 v[18:19], v[12:13], v[10:11]
	v_lshlrev_b32_e32 v12, 16, v16
	v_and_b32_e32 v13, 0xffff0000, v16
	v_lshlrev_b32_e32 v10, 16, v17
	v_and_b32_e32 v11, 0xffff0000, v17
	v_lshlrev_b32_e32 v16, 16, v14
	v_and_b32_e32 v17, 0xffff0000, v14
	v_lshlrev_b32_e32 v14, 16, v15
	v_and_b32_e32 v15, 0xffff0000, v15
	v_pk_add_f32 v[12:13], v[12:13], v[16:17]
	v_pk_add_f32 v[10:11], v[10:11], v[14:15]
	v_mul_f32_e32 v16, v12, v12
	v_pk_add_f32 v[14:15], v[34:35], v[34:35] op_sel:[0,1] op_sel_hi:[1,0]
	v_pk_add_f32 v[20:21], v[20:21], v[40:41]
	v_mov_b32_e32 v15, v16
	v_pk_add_f32 v[16:17], v[32:33], v[32:33] op_sel:[0,1] op_sel_hi:[1,0]
	v_or_b32_e32 v32, 0x3200, v22
	v_mov_b32_e32 v33, v23
	v_mul_f32_e32 v40, v13, v13
	v_lshl_add_u64 v[34:35], s[82:83], 0, v[32:33]
	v_lshl_add_u64 v[32:33], s[80:81], 0, v[32:33]
	v_mov_b32_e32 v17, v40
	global_load_dwordx2 v[34:35], v[34:35], off nt
	v_pk_add_f32 v[14:15], v[14:15], v[16:17]
	global_load_dwordx2 v[40:41], v[32:33], off nt
	v_mul_f32_e32 v16, v21, v21
	v_mul_f32_e32 v32, v19, v19
	v_mul_f32_e32 v44, v10, v10
	v_mul_f32_e32 v45, v11, v11
	v_pk_fma_f32 v[16:17], v[20:21], v[20:21], v[16:17] op_sel_hi:[1,1,0]
	v_pk_fma_f32 v[32:33], v[18:19], v[18:19], v[32:33] op_sel_hi:[1,1,0]
	v_mov_b32_e32 v17, v44
	v_mov_b32_e32 v33, v45
	v_pk_add_f32 v[16:17], v[16:17], v[32:33]
	v_or_b32_e32 v32, 0x4000, v22
	v_pk_add_f32 v[44:45], v[14:15], v[16:17]
	s_waitcnt vmcnt(8)
	v_lshlrev_b32_e32 v14, 16, v26
	v_and_b32_e32 v15, 0xffff0000, v26
	v_lshlrev_b32_e32 v16, 16, v27
	v_and_b32_e32 v17, 0xffff0000, v27
	s_waitcnt vmcnt(7)
	v_lshlrev_b32_e32 v26, 16, v30
	v_and_b32_e32 v27, 0xffff0000, v30
	v_lshlrev_b32_e32 v30, 16, v31
	v_and_b32_e32 v31, 0xffff0000, v31
	v_pk_add_f32 v[14:15], v[14:15], v[26:27]
	v_pk_add_f32 v[16:17], v[16:17], v[30:31]
	v_pk_mul_f32 v[30:31], v[14:15], v[14:15]
	v_pk_mul_f32 v[26:27], v[16:17], v[16:17]
	v_mov_b32_e32 v33, v23
	v_pk_mov_b32 v[48:49], v[30:31], v[26:27] op_sel:[1,0]
	v_mov_b32_e32 v31, v27
	v_pk_add_f32 v[48:49], v[48:49], v[30:31]
	v_lshl_add_u64 v[30:31], s[80:81], 0, v[32:33]
	v_lshl_add_u64 v[46:47], s[82:83], 0, v[32:33]
	global_load_dwordx2 v[50:51], v[30:31], off nt
	v_or_b32_e32 v30, 0x4200, v22
	v_mov_b32_e32 v31, v23
	global_load_dwordx2 v[46:47], v[46:47], off nt
	v_lshl_add_u64 v[32:33], s[82:83], 0, v[30:31]
	v_lshl_add_u64 v[30:31], s[80:81], 0, v[30:31]
	global_load_dwordx2 v[52:53], v[32:33], off nt
	global_load_dwordx2 v[54:55], v[30:31], off nt
	s_waitcnt vmcnt(10)
; __device__ __forceinline__ f32x4 ld_bf4(const bf16_t* p) { u32x2 w = *(const u32x2*)p; return (f32x4){__uint_as_float(w.x << 16), __uint_as_float(w.x & 0xffff0000u), __uint_as_float(w.y << 16), __uint_as_float(w.y & 0xffff0000u)}; }
; __global__ void __launch_bounds__(NTHR, 2) fwd_kernel(Args a) {
;     ...
;         for (int t = 0; t < 16; ++t) { const size_t o = ((((((size_t)(b * 32 + n) * 4 + h) * 8 + (t >> 1)) * 4 + ct) * 2 + (t & 1)) * 64 + lane) << 2;
;             const f32x4 x = ld_bf4(Of + o) + ld_bf4(Ob + o); ov[t] = x; ss += (x[0] * x[0] + x[1] * x[1]) + (x[2] * x[2] + x[3] * x[3]); }
;         ss += __shfl_xor(ss, 16); ss += __shfl_xor(ss, 32);
	v_lshlrev_b32_e32 v26, 16, v28
	v_and_b32_e32 v27, 0xffff0000, v28
	v_lshlrev_b32_e32 v28, 16, v29
	v_and_b32_e32 v29, 0xffff0000, v29
	s_waitcnt vmcnt(8)
	v_lshlrev_b32_e32 v32, 16, v38
	v_and_b32_e32 v33, 0xffff0000, v38
	v_lshlrev_b32_e32 v30, 16, v39
	v_and_b32_e32 v31, 0xffff0000, v39
	v_pk_add_f32 v[30:31], v[28:29], v[30:31]
	v_pk_add_f32 v[32:33], v[26:27], v[32:33]
	s_waitcnt vmcnt(7)
	v_lshlrev_b32_e32 v28, 16, v36
	v_and_b32_e32 v29, 0xffff0000, v36
	v_lshlrev_b32_e32 v26, 16, v37
	v_and_b32_e32 v27, 0xffff0000, v37
	s_waitcnt vmcnt(6)
	v_lshlrev_b32_e32 v36, 16, v42
	v_and_b32_e32 v37, 0xffff0000, v42
	v_lshlrev_b32_e32 v38, 16, v43
	v_and_b32_e32 v39, 0xffff0000, v43
	v_pk_add_f32 v[28:29], v[28:29], v[36:37]
	v_pk_add_f32 v[26:27], v[26:27], v[38:39]
	v_mul_f32_e32 v38, v28, v28
	v_pk_add_f32 v[36:37], v[44:45], v[44:45] op_sel:[0,1] op_sel_hi:[1,0]
	v_mul_f32_e32 v42, v29, v29
	v_mov_b32_e32 v37, v38
	v_pk_add_f32 v[38:39], v[48:49], v[48:49] op_sel:[0,1] op_sel_hi:[1,0]
	v_mul_f32_e32 v43, v26, v26
	v_mov_b32_e32 v39, v42
	v_pk_add_f32 v[36:37], v[36:37], v[38:39]
	v_mul_f32_e32 v38, v33, v33
	v_pk_fma_f32 v[38:39], v[32:33], v[32:33], v[38:39] op_sel_hi:[1,1,0]
	v_mul_f32_e32 v42, v31, v31
	v_mul_f32_e32 v56, v27, v27
	v_mov_b32_e32 v39, v43
	v_pk_fma_f32 v[42:43], v[30:31], v[30:31], v[42:43] op_sel_hi:[1,1,0]
	s_nop 0
	v_mov_b32_e32 v43, v56
	v_pk_add_f32 v[38:39], v[38:39], v[42:43]
	v_or_b32_e32 v42, 0x5000, v22
	v_mov_b32_e32 v43, v23
	v_lshl_add_u64 v[44:45], s[82:83], 0, v[42:43]
	v_pk_add_f32 v[56:57], v[36:37], v[38:39]
	s_waitcnt vmcnt(5)
	v_lshlrev_b32_e32 v36, 16, v34
	v_and_b32_e32 v37, 0xffff0000, v34
	v_lshlrev_b32_e32 v34, 16, v35
	v_and_b32_e32 v35, 0xffff0000, v35
	s_waitcnt vmcnt(4)
	v_lshlrev_b32_e32 v38, 16, v40
	v_and_b32_e32 v39, 0xffff0000, v40
	v_lshl_add_u64 v[42:43], s[80:81], 0, v[42:43]
	v_lshlrev_b32_e32 v40, 16, v41
	v_and_b32_e32 v41, 0xffff0000, v41
	global_load_dwordx2 v[48:49], v[44:45], off nt
	global_load_dwordx2 v[58:59], v[42:43], off nt
	v_pk_add_f32 v[42:43], v[36:37], v[38:39]
	v_pk_add_f32 v[44:45], v[34:35], v[40:41]
	v_pk_mul_f32 v[36:37], v[42:43], v[42:43]
	v_pk_mul_f32 v[34:35], v[44:45], v[44:45]
	v_or_b32_e32 v40, 0x5200, v22
	v_pk_mov_b32 v[38:39], v[36:37], v[34:35] op_sel:[1,0]
	v_mov_b32_e32 v41, v23
	v_mov_b32_e32 v37, v35
	v_lshl_add_u64 v[60:61], s[82:83], 0, v[40:41]
	v_pk_add_f32 v[62:63], v[38:39], v[36:37]
	v_lshl_add_u64 v[34:35], s[80:81], 0, v[40:41]
	v_or_b32_e32 v36, 0x6000, v22
	v_mov_b32_e32 v37, v23
	global_load_dwordx2 v[60:61], v[60:61], off nt
	v_lshl_add_u64 v[38:39], s[82:83], 0, v[36:37]
	global_load_dwordx2 v[72:73], v[34:35], off nt
	global_load_dwordx2 v[74:75], v[38:39], off nt
	v_lshl_add_u64 v[36:37], s[80:81], 0, v[36:37]
	s_waitcnt vmcnt(8)
	v_lshlrev_b32_e32 v40, 16, v51
	v_and_b32_e32 v41, 0xffff0000, v51
	s_waitcnt vmcnt(7)
	v_lshlrev_b32_e32 v34, 16, v46
	v_and_b32_e32 v35, 0xffff0000, v46
	v_lshlrev_b32_e32 v38, 16, v47
	v_and_b32_e32 v39, 0xffff0000, v47
	global_load_dwordx2 v[46:47], v[36:37], off nt
	v_lshlrev_b32_e32 v36, 16, v50
	v_and_b32_e32 v37, 0xffff0000, v50
	v_pk_add_f32 v[38:39], v[38:39], v[40:41]
	v_pk_add_f32 v[40:41], v[34:35], v[36:37]
	s_waitcnt vmcnt(7)
	v_lshlrev_b32_e32 v36, 16, v52
	v_and_b32_e32 v37, 0xffff0000, v52
	s_waitcnt vmcnt(6)
	v_lshlrev_b32_e32 v50, 16, v54
	v_and_b32_e32 v51, 0xffff0000, v54
	v_pk_add_f32 v[36:37], v[36:37], v[50:51]
	v_lshlrev_b32_e32 v34, 16, v53
	v_and_b32_e32 v35, 0xffff0000, v53
	v_lshlrev_b32_e32 v52, 16, v55
	v_and_b32_e32 v53, 0xffff0000, v55
	v_mul_f32_e32 v64, v36, v36
	v_mul_f32_e32 v65, v37, v37
	v_pk_add_f32 v[54:55], v[56:57], v[56:57] op_sel:[0,1] op_sel_hi:[1,0]
	v_pk_add_f32 v[56:57], v[62:63], v[62:63] op_sel:[0,1] op_sel_hi:[1,0]
	v_mov_b32_e32 v55, v64
	v_mov_b32_e32 v57, v65
	v_pk_add_f32 v[34:35], v[34:35], v[52:53]
	v_pk_add_f32 v[54:55], v[54:55], v[56:57]
	v_mul_f32_e32 v56, v41, v41
	v_mul_f32_e32 v62, v39, v39
	v_mul_f32_e32 v66, v34, v34
	v_mul_f32_e32 v78, v35, v35
	v_pk_fma_f32 v[56:57], v[40:41], v[40:41], v[56:57] op_sel_hi:[1,1,0]
	v_pk_fma_f32 v[62:63], v[38:39], v[38:39], v[62:63] op_sel_hi:[1,1,0]
	v_or_b32_e32 v50, 0x6200, v22
	v_mov_b32_e32 v51, v23
	v_mov_b32_e32 v57, v66
	v_or_b32_e32 v64, 0x7000, v22
	v_mov_b32_e32 v65, v23
	v_mov_b32_e32 v63, v78
	v_lshl_add_u64 v[52:53], s[82:83], 0, v[50:51]
	v_lshl_add_u64 v[50:51], s[80:81], 0, v[50:51]
	v_pk_add_f32 v[56:57], v[56:57], v[62:63]
	v_lshl_add_u64 v[62:63], s[80:81], 0, v[64:65]
	global_load_dwordx2 v[52:53], v[52:53], off nt
	v_lshl_add_u64 v[66:67], s[82:83], 0, v[64:65]
	global_load_dwordx2 v[78:79], v[62:63], off nt
	v_or_b32_e32 v22, 0x7200, v22
	global_load_dwordx2 v[50:51], v[50:51], off nt
	v_lshl_add_u64 v[62:63], s[82:83], 0, v[22:23]
	global_load_dwordx2 v[76:77], v[66:67], off nt
	global_load_dwordx2 v[80:81], v[62:63], off nt
	v_lshl_add_u64 v[22:23], s[80:81], 0, v[22:23]
	global_load_dwordx2 v[82:83], v[22:23], off nt
	v_pk_add_f32 v[54:55], v[54:55], v[56:57]
	s_waitcnt vmcnt(11)
	v_lshlrev_b32_e32 v56, 16, v48
	v_and_b32_e32 v57, 0xffff0000, v48
	v_lshlrev_b32_e32 v48, 16, v49
	v_and_b32_e32 v49, 0xffff0000, v49
	s_waitcnt vmcnt(10)
	v_lshlrev_b32_e32 v22, 16, v58
	v_and_b32_e32 v23, 0xffff0000, v58
	v_lshlrev_b32_e32 v58, 16, v59
	v_and_b32_e32 v59, 0xffff0000, v59
	v_pk_add_f32 v[64:65], v[56:57], v[22:23]
	v_pk_add_f32 v[66:67], v[48:49], v[58:59]
	v_pk_mul_f32 v[48:49], v[64:65], v[64:65]
	v_pk_mul_f32 v[22:23], v[66:67], v[66:67]
	v_pk_add_f32 v[54:55], v[54:55], v[54:55] op_sel:[0,1] op_sel_hi:[1,0]
	v_pk_mov_b32 v[56:57], v[48:49], v[22:23] op_sel:[1,0]
	v_mov_b32_e32 v49, v23
	v_pk_add_f32 v[48:49], v[56:57], v[48:49]
	s_waitcnt vmcnt(9)
; __device__ __forceinline__ f32x4 ld_bf4(const bf16_t* p) { u32x2 w = *(const u32x2*)p; return (f32x4){__uint_as_float(w.x << 16), __uint_as_float(w.x & 0xffff0000u), __uint_as_float(w.y << 16), __uint_as_float(w.y & 0xffff0000u)}; }
; __device__ __forceinline__ void st_bf4(bf16_t* p, f32x4 v) { u32x2 w; w.x = pk2(v[0], v[1]); w.y = pk2(v[2], v[3]); *(u32x2*)p = w; }
; __global__ void __launch_bounds__(NTHR, 2) fwd_kernel(Args a) {
;     ...
;         for (int t = 0; t < 16; ++t) { const size_t o = ((((((size_t)(b * 32 + n) * 4 + h) * 8 + (t >> 1)) * 4 + ct) * 2 + (t & 1)) * 64 + lane) << 2;
;             const f32x4 x = ld_bf4(Of + o) + ld_bf4(Ob + o); ov[t] = x; ss += (x[0] * x[0] + x[1] * x[1]) + (x[2] * x[2] + x[3] * x[3]); }
;         ss += __shfl_xor(ss, 16); ss += __shfl_xor(ss, 32);
;         const float rstd = rsqrtf(ss * (1.0f / DV) + EPS);
;         const size_t ro = (size_t)(b * SEQ + n * 64 + 16 * ct + fr) * VW + h * DV + 4 * fq;
; #pragma unroll
;         for (int t = 0; t < 16; ++t) { const f32x4 gg = *(const f32x4*)(a.in[I_GGLA] + h * DV + t * 16 + 4 * fq);
;             st_bf4(AG + ro + t * 16, ld_bf4(Rb + ro + t * 16) * (ov[t] * rstd * gg)); }
	v_lshlrev_b32_e32 v22, 16, v60
	v_and_b32_e32 v23, 0xffff0000, v60
	v_lshlrev_b32_e32 v56, 16, v61
	v_and_b32_e32 v57, 0xffff0000, v61
	s_waitcnt vmcnt(8)
	v_lshlrev_b32_e32 v58, 16, v72
	v_and_b32_e32 v59, 0xffff0000, v72
	v_lshlrev_b32_e32 v60, 16, v73
	v_and_b32_e32 v61, 0xffff0000, v73
	v_pk_add_f32 v[60:61], v[56:57], v[60:61]
	v_pk_add_f32 v[62:63], v[22:23], v[58:59]
	s_waitcnt vmcnt(7)
	v_lshlrev_b32_e32 v56, 16, v74
	v_and_b32_e32 v57, 0xffff0000, v74
	v_lshlrev_b32_e32 v22, 16, v75
	v_and_b32_e32 v23, 0xffff0000, v75
	global_load_dwordx4 v[72:75], v69, s[2:3] nt
	s_waitcnt vmcnt(7)
	v_lshlrev_b32_e32 v58, 16, v46
	v_and_b32_e32 v59, 0xffff0000, v46
	v_lshlrev_b32_e32 v46, 16, v47
	v_and_b32_e32 v47, 0xffff0000, v47
	v_pk_add_f32 v[22:23], v[22:23], v[46:47]
	v_pk_add_f32 v[46:47], v[56:57], v[58:59]
	v_pk_add_f32 v[48:49], v[48:49], v[48:49] op_sel:[0,1] op_sel_hi:[1,0]
	v_mul_f32_e32 v56, v46, v46
	v_mul_f32_e32 v57, v47, v47
	v_mov_b32_e32 v55, v56
	v_mov_b32_e32 v49, v57
	v_pk_add_f32 v[48:49], v[54:55], v[48:49]
	v_mul_f32_e32 v54, v63, v63
	v_mul_f32_e32 v56, v61, v61
	v_mul_f32_e32 v58, v22, v22
	v_mul_f32_e32 v59, v23, v23
	v_pk_fma_f32 v[54:55], v[62:63], v[62:63], v[54:55] op_sel_hi:[1,1,0]
	v_pk_fma_f32 v[56:57], v[60:61], v[60:61], v[56:57] op_sel_hi:[1,1,0]
	v_mov_b32_e32 v55, v58
	v_mov_b32_e32 v57, v59
	v_pk_add_f32 v[54:55], v[54:55], v[56:57]
	s_waitcnt vmcnt(5)
	v_lshlrev_b32_e32 v58, 16, v78
	v_pk_add_f32 v[84:85], v[48:49], v[54:55]
	v_lshlrev_b32_e32 v48, 16, v52
	v_and_b32_e32 v49, 0xffff0000, v52
	v_lshlrev_b32_e32 v54, 16, v53
	v_and_b32_e32 v55, 0xffff0000, v53
	s_waitcnt vmcnt(4)
	v_lshlrev_b32_e32 v52, 16, v50
	v_and_b32_e32 v53, 0xffff0000, v50
	v_lshlrev_b32_e32 v50, 16, v51
	v_and_b32_e32 v51, 0xffff0000, v51
	v_pk_add_f32 v[52:53], v[48:49], v[52:53]
	v_pk_add_f32 v[54:55], v[54:55], v[50:51]
	v_pk_mul_f32 v[50:51], v[52:53], v[52:53]
	v_pk_mul_f32 v[48:49], v[54:55], v[54:55]
	v_and_b32_e32 v59, 0xffff0000, v78
	v_pk_mov_b32 v[56:57], v[50:51], v[48:49] op_sel:[1,0]
	v_mov_b32_e32 v51, v49
	v_pk_add_f32 v[88:89], v[56:57], v[50:51]
	s_waitcnt vmcnt(3)
	v_lshlrev_b32_e32 v50, 16, v77
	v_and_b32_e32 v51, 0xffff0000, v77
	v_lshlrev_b32_e32 v56, 16, v79
	v_and_b32_e32 v57, 0xffff0000, v79
	v_lshlrev_b32_e32 v48, 16, v76
	v_and_b32_e32 v49, 0xffff0000, v76
	v_pk_add_f32 v[56:57], v[50:51], v[56:57]
	s_waitcnt vmcnt(2)
	v_lshlrev_b32_e32 v50, 16, v80
	v_and_b32_e32 v51, 0xffff0000, v80
	s_waitcnt vmcnt(1)
	v_lshlrev_b32_e32 v76, 16, v82
	v_and_b32_e32 v77, 0xffff0000, v82
	v_pk_add_f32 v[58:59], v[48:49], v[58:59]
	v_lshlrev_b32_e32 v48, 16, v81
	v_and_b32_e32 v49, 0xffff0000, v81
	v_lshlrev_b32_e32 v78, 16, v83
	v_and_b32_e32 v79, 0xffff0000, v83
	v_pk_add_f32 v[50:51], v[50:51], v[76:77]
	v_pk_add_f32 v[48:49], v[48:49], v[78:79]
	v_mul_f32_e32 v78, v50, v50
	v_pk_add_f32 v[76:77], v[84:85], v[84:85] op_sel:[0,1] op_sel_hi:[1,0]
	v_mul_f32_e32 v80, v51, v51
	v_mov_b32_e32 v77, v78
	v_pk_add_f32 v[78:79], v[88:89], v[88:89] op_sel:[0,1] op_sel_hi:[1,0]
	v_mul_f32_e32 v81, v48, v48
	v_mov_b32_e32 v79, v80
	v_pk_add_f32 v[76:77], v[76:77], v[78:79]
	v_mul_f32_e32 v78, v59, v59
	v_pk_fma_f32 v[78:79], v[58:59], v[58:59], v[78:79] op_sel_hi:[1,1,0]
	v_mul_f32_e32 v80, v57, v57
	v_mul_f32_e32 v82, v49, v49
	v_mov_b32_e32 v79, v81
	v_pk_fma_f32 v[80:81], v[56:57], v[56:57], v[80:81] op_sel_hi:[1,1,0]
	v_and_b32_e32 v83, 0xffff0000, v87
	v_mov_b32_e32 v81, v82
	v_pk_add_f32 v[78:79], v[78:79], v[80:81]
	v_lshlrev_b32_e32 v80, 16, v86
	v_pk_add_f32 v[76:77], v[76:77], v[78:79]
	v_and_b32_e32 v81, 0xffff0000, v86
	v_add_f32_e32 v76, v76, v77
	ds_bpermute_b32 v71, v71, v76
	v_xor_b32_e32 v77, 32, v68
	v_cmp_lt_i32_e32 vcc, v77, v70
	v_lshlrev_b32_e32 v82, 16, v87
	s_waitcnt lgkmcnt(0)
	v_add_f32_e32 v70, v76, v71
	v_cndmask_b32_e32 v68, v68, v77, vcc
	v_lshlrev_b32_e32 v68, 2, v68
	ds_bpermute_b32 v68, v68, v70
	s_waitcnt lgkmcnt(0)
	v_add_f32_e32 v68, v70, v68
	v_mov_b32_e32 v70, 0x358637bd
	v_fmac_f32_e32 v70, 0x3b800000, v68
	v_mul_f32_e32 v68, 0x4b800000, v70
	v_cmp_gt_f32_e32 vcc, s4, v70
	s_nop 1
	v_cndmask_b32_e32 v68, v70, v68, vcc
	v_rsq_f32_e32 v68, v68
	s_nop 0
	v_mul_f32_e32 v70, 0x45800000, v68
	v_cndmask_b32_e32 v68, v68, v70, vcc
	v_pk_mul_f32 v[4:5], v[68:69], v[4:5] op_sel_hi:[0,1]
	v_pk_mul_f32 v[2:3], v[68:69], v[2:3] op_sel_hi:[0,1]
	global_load_dwordx2 v[96:97], v[0:1], off offset:32 nt
	global_load_dwordx2 v[98:99], v[0:1], off offset:64 nt
	global_load_dwordx2 v[100:101], v[0:1], off offset:96 nt
	global_load_dwordx4 v[102:105], v69, s[2:3] offset:64 nt
	global_load_dwordx4 v[106:109], v69, s[2:3] offset:128 nt
	global_load_dwordx4 v[110:113], v69, s[2:3] offset:192 nt
	global_load_dwordx2 v[114:115], v[0:1], off offset:128 nt
	global_load_dwordx4 v[116:119], v69, s[2:3] offset:256 nt
	global_load_dwordx2 v[120:121], v[0:1], off offset:160 nt
	global_load_dwordx2 v[122:123], v[0:1], off offset:192 nt
	global_load_dwordx2 v[124:125], v[0:1], off offset:224 nt
	global_load_dwordx4 v[126:129], v69, s[2:3] offset:320 nt
	global_load_dwordx4 v[130:133], v69, s[2:3] offset:384 nt
	global_load_dwordx4 v[134:137], v69, s[2:3] offset:448 nt
	global_load_dwordx2 v[138:139], v[0:1], off offset:256 nt
	global_load_dwordx4 v[140:143], v69, s[2:3] offset:512 nt
	global_load_dwordx2 v[144:145], v[0:1], off offset:288 nt
	global_load_dwordx2 v[146:147], v[0:1], off offset:320 nt
	global_load_dwordx2 v[148:149], v[0:1], off offset:352 nt
	global_load_dwordx4 v[150:153], v69, s[2:3] offset:576 nt
	global_load_dwordx4 v[154:157], v69, s[2:3] offset:640 nt
	global_load_dwordx4 v[158:161], v69, s[2:3] offset:704 nt
	global_load_dwordx2 v[162:163], v[0:1], off offset:384 nt
	global_load_dwordx4 v[164:167], v69, s[2:3] offset:768 nt
	global_load_dwordx2 v[168:169], v[0:1], off offset:416 nt
	global_load_dwordx2 v[170:171], v[0:1], off offset:448 nt
	global_load_dwordx2 v[172:173], v[0:1], off offset:480 nt
	global_load_dwordx4 v[174:177], v69, s[2:3] offset:832 nt
	global_load_dwordx4 v[178:181], v69, s[2:3] offset:896 nt
	global_load_dwordx4 v[182:185], v69, s[2:3] offset:960 nt
	s_waitcnt vmcnt(0)
; __device__ __forceinline__ f32x4 ld_bf4(const bf16_t* p) { u32x2 w = *(const u32x2*)p; return (f32x4){__uint_as_float(w.x << 16), __uint_as_float(w.x & 0xffff0000u), __uint_as_float(w.y << 16), __uint_as_float(w.y & 0xffff0000u)}; }
; __device__ __forceinline__ void st_bf4(bf16_t* p, f32x4 v) { u32x2 w; w.x = pk2(v[0], v[1]); w.y = pk2(v[2], v[3]); *(u32x2*)p = w; }
; __global__ void __launch_bounds__(NTHR, 2) fwd_kernel(Args a) {
;     ...
;         const size_t ro = (size_t)(b * SEQ + n * 64 + 16 * ct + fr) * VW + h * DV + 4 * fq;
; #pragma unroll
;         for (int t = 0; t < 16; ++t) { const f32x4 gg = *(const f32x4*)(a.in[I_GGLA] + h * DV + t * 16 + 4 * fq);
;             st_bf4(AG + ro + t * 16, ld_bf4(Rb + ro + t * 16) * (ov[t] * rstd * gg)); }
	v_pk_mul_f32 v[2:3], v[72:73], v[2:3]
	v_pk_mul_f32 v[4:5], v[74:75], v[4:5]
	v_pk_mul_f32 v[2:3], v[2:3], v[80:81]
	v_pk_mul_f32 v[4:5], v[4:5], v[82:83]
	v_cvt_pk_bf16_f32 v2, v2, v3
	v_cvt_pk_bf16_f32 v3, v4, v5
	v_pk_mul_f32 v[8:9], v[68:69], v[8:9] op_sel_hi:[0,1]
	global_store_dwordx2 v[24:25], v[2:3], off
	v_pk_mul_f32 v[6:7], v[68:69], v[6:7] op_sel_hi:[0,1]
	v_pk_mul_f32 v[18:19], v[68:69], v[18:19] op_sel_hi:[0,1]
	v_pk_mul_f32 v[20:21], v[68:69], v[20:21] op_sel_hi:[0,1]
	v_pk_mul_f32 v[10:11], v[68:69], v[10:11] op_sel_hi:[0,1]
	v_pk_mul_f32 v[12:13], v[68:69], v[12:13] op_sel_hi:[0,1]
	v_pk_mul_f32 v[16:17], v[68:69], v[16:17] op_sel_hi:[0,1]
	v_pk_mul_f32 v[14:15], v[68:69], v[14:15] op_sel_hi:[0,1]
	s_nop 0
	v_lshlrev_b32_e32 v72, 16, v96
	v_and_b32_e32 v73, 0xffff0000, v96
	v_lshlrev_b32_e32 v70, 16, v97
	v_and_b32_e32 v71, 0xffff0000, v97
	s_nop 0
	v_pk_mul_f32 v[2:3], v[102:103], v[6:7]
	v_pk_mul_f32 v[4:5], v[104:105], v[8:9]
	v_pk_mul_f32 v[2:3], v[2:3], v[72:73]
	v_pk_mul_f32 v[4:5], v[4:5], v[70:71]
	v_cvt_pk_bf16_f32 v2, v2, v3
	v_cvt_pk_bf16_f32 v3, v4, v5
	global_store_dwordx2 v[24:25], v[2:3], off offset:32
	v_lshlrev_b32_e32 v6, 16, v98
	v_and_b32_e32 v7, 0xffff0000, v98
	v_lshlrev_b32_e32 v8, 16, v99
	v_and_b32_e32 v9, 0xffff0000, v99
	s_nop 0
	v_pk_mul_f32 v[2:3], v[106:107], v[20:21]
	v_pk_mul_f32 v[4:5], v[108:109], v[18:19]
	v_pk_mul_f32 v[2:3], v[2:3], v[6:7]
	v_pk_mul_f32 v[4:5], v[4:5], v[8:9]
	v_cvt_pk_bf16_f32 v2, v2, v3
	v_cvt_pk_bf16_f32 v3, v4, v5
	global_store_dwordx2 v[24:25], v[2:3], off offset:64
	v_lshlrev_b32_e32 v6, 16, v100
	v_and_b32_e32 v7, 0xffff0000, v100
	v_lshlrev_b32_e32 v8, 16, v101
	v_and_b32_e32 v9, 0xffff0000, v101
	s_nop 0
	v_pk_mul_f32 v[2:3], v[110:111], v[12:13]
	v_pk_mul_f32 v[4:5], v[112:113], v[10:11]
	v_pk_mul_f32 v[4:5], v[4:5], v[8:9]
	v_pk_mul_f32 v[2:3], v[2:3], v[6:7]
	s_nop 0
	v_lshlrev_b32_e32 v18, 16, v114
	v_cvt_pk_bf16_f32 v2, v2, v3
	v_cvt_pk_bf16_f32 v3, v4, v5
	global_store_dwordx2 v[24:25], v[2:3], off offset:96
	s_nop 0
	v_and_b32_e32 v19, 0xffff0000, v114
	v_lshlrev_b32_e32 v10, 16, v115
	v_and_b32_e32 v11, 0xffff0000, v115
	s_nop 0
	v_pk_mul_f32 v[2:3], v[116:117], v[14:15]
	v_pk_mul_f32 v[4:5], v[118:119], v[16:17]
	v_pk_mul_f32 v[2:3], v[2:3], v[18:19]
	v_pk_mul_f32 v[4:5], v[4:5], v[10:11]
	v_cvt_pk_bf16_f32 v2, v2, v3
	v_cvt_pk_bf16_f32 v3, v4, v5
	global_store_dwordx2 v[24:25], v[2:3], off offset:128
	v_pk_mul_f32 v[14:15], v[68:69], v[30:31] op_sel_hi:[0,1]
	v_pk_mul_f32 v[16:17], v[68:69], v[32:33] op_sel_hi:[0,1]
	s_nop 0
	v_lshlrev_b32_e32 v10, 16, v120
	v_and_b32_e32 v11, 0xffff0000, v120
	v_lshlrev_b32_e32 v6, 16, v121
	v_and_b32_e32 v7, 0xffff0000, v121
	v_pk_mul_f32 v[18:19], v[68:69], v[40:41] op_sel_hi:[0,1]
	s_nop 0
	v_pk_mul_f32 v[2:3], v[126:127], v[16:17]
	v_pk_mul_f32 v[4:5], v[128:129], v[14:15]
	v_pk_mul_f32 v[2:3], v[2:3], v[10:11]
	v_pk_mul_f32 v[4:5], v[4:5], v[6:7]
	v_cvt_pk_bf16_f32 v2, v2, v3
	v_cvt_pk_bf16_f32 v3, v4, v5
	global_store_dwordx2 v[24:25], v[2:3], off offset:160
	v_pk_mul_f32 v[10:11], v[68:69], v[26:27] op_sel_hi:[0,1]
	v_pk_mul_f32 v[14:15], v[68:69], v[28:29] op_sel_hi:[0,1]
	v_lshlrev_b32_e32 v6, 16, v122
	v_and_b32_e32 v7, 0xffff0000, v122
	v_lshlrev_b32_e32 v8, 16, v123
	v_and_b32_e32 v9, 0xffff0000, v123
	v_pk_mul_f32 v[16:17], v[68:69], v[38:39] op_sel_hi:[0,1]
	s_nop 0
	v_pk_mul_f32 v[2:3], v[130:131], v[14:15]
	v_pk_mul_f32 v[4:5], v[132:133], v[10:11]
	v_pk_mul_f32 v[2:3], v[2:3], v[6:7]
	v_pk_mul_f32 v[4:5], v[4:5], v[8:9]
	v_cvt_pk_bf16_f32 v2, v2, v3
	v_cvt_pk_bf16_f32 v3, v4, v5
	global_store_dwordx2 v[24:25], v[2:3], off offset:192
	s_nop 0
	v_lshlrev_b32_e32 v8, 16, v124
	v_and_b32_e32 v9, 0xffff0000, v124
	v_lshlrev_b32_e32 v10, 16, v125
	v_and_b32_e32 v11, 0xffff0000, v125
	v_pk_mul_f32 v[12:13], v[68:69], v[44:45] op_sel_hi:[0,1]
	v_pk_mul_f32 v[14:15], v[68:69], v[42:43] op_sel_hi:[0,1]
	s_nop 0
	v_pk_mul_f32 v[2:3], v[134:135], v[14:15]
	v_pk_mul_f32 v[4:5], v[136:137], v[12:13]
	v_pk_mul_f32 v[2:3], v[2:3], v[8:9]
	v_pk_mul_f32 v[4:5], v[4:5], v[10:11]
	v_cvt_pk_bf16_f32 v2, v2, v3
	v_cvt_pk_bf16_f32 v3, v4, v5
	global_store_dwordx2 v[24:25], v[2:3], off offset:224
	s_nop 0
	s_nop 0
; __device__ __forceinline__ f32x4 ld_bf4(const bf16_t* p) { u32x2 w = *(const u32x2*)p; return (f32x4){__uint_as_float(w.x << 16), __uint_as_float(w.x & 0xffff0000u), __uint_as_float(w.y << 16), __uint_as_float(w.y & 0xffff0000u)}; }
; __device__ __forceinline__ void st_bf4(bf16_t* p, f32x4 v) { u32x2 w; w.x = pk2(v[0], v[1]); w.y = pk2(v[2], v[3]); *(u32x2*)p = w; }
; __global__ void __launch_bounds__(NTHR, 2) fwd_kernel(Args a) {
;     ...
;         const size_t ro = (size_t)(b * SEQ + n * 64 + 16 * ct + fr) * VW + h * DV + 4 * fq;
; #pragma unroll
;         for (int t = 0; t < 16; ++t) { const f32x4 gg = *(const f32x4*)(a.in[I_GGLA] + h * DV + t * 16 + 4 * fq);
;             st_bf4(AG + ro + t * 16, ld_bf4(Rb + ro + t * 16) * (ov[t] * rstd * gg)); }
	v_lshlrev_b32_e32 v14, 16, v138
	v_and_b32_e32 v15, 0xffff0000, v138
	v_lshlrev_b32_e32 v6, 16, v139
	v_and_b32_e32 v7, 0xffff0000, v139
	s_nop 0
	v_pk_mul_f32 v[2:3], v[140:141], v[18:19]
	v_pk_mul_f32 v[4:5], v[142:143], v[16:17]
	v_pk_mul_f32 v[2:3], v[2:3], v[14:15]
	v_pk_mul_f32 v[4:5], v[4:5], v[6:7]
	v_cvt_pk_bf16_f32 v2, v2, v3
	v_cvt_pk_bf16_f32 v3, v4, v5
	global_store_dwordx2 v[24:25], v[2:3], off offset:256
	v_pk_mul_f32 v[14:15], v[68:69], v[34:35] op_sel_hi:[0,1]
	v_pk_mul_f32 v[16:17], v[68:69], v[36:37] op_sel_hi:[0,1]
	s_nop 0
	v_lshlrev_b32_e32 v6, 16, v144
	v_and_b32_e32 v7, 0xffff0000, v144
	v_lshlrev_b32_e32 v8, 16, v145
	v_and_b32_e32 v9, 0xffff0000, v145
	s_nop 0
	v_pk_mul_f32 v[2:3], v[150:151], v[16:17]
	v_pk_mul_f32 v[4:5], v[152:153], v[14:15]
	v_pk_mul_f32 v[2:3], v[2:3], v[6:7]
	v_pk_mul_f32 v[4:5], v[4:5], v[8:9]
	v_cvt_pk_bf16_f32 v2, v2, v3
	v_cvt_pk_bf16_f32 v3, v4, v5
	global_store_dwordx2 v[24:25], v[2:3], off offset:288
	v_lshlrev_b32_e32 v6, 16, v146
	v_and_b32_e32 v7, 0xffff0000, v146
	v_lshlrev_b32_e32 v8, 16, v147
	v_and_b32_e32 v9, 0xffff0000, v147
	v_pk_mul_f32 v[10:11], v[68:69], v[66:67] op_sel_hi:[0,1]
	v_pk_mul_f32 v[14:15], v[68:69], v[64:65] op_sel_hi:[0,1]
	v_pk_mul_f32 v[16:17], v[68:69], v[46:47] op_sel_hi:[0,1]
	s_nop 0
	v_pk_mul_f32 v[2:3], v[154:155], v[14:15]
	v_pk_mul_f32 v[4:5], v[156:157], v[10:11]
	v_pk_mul_f32 v[2:3], v[2:3], v[6:7]
	v_pk_mul_f32 v[4:5], v[4:5], v[8:9]
	v_cvt_pk_bf16_f32 v2, v2, v3
	v_cvt_pk_bf16_f32 v3, v4, v5
	global_store_dwordx2 v[24:25], v[2:3], off offset:320
	s_nop 0
	v_lshlrev_b32_e32 v8, 16, v148
	v_and_b32_e32 v9, 0xffff0000, v148
	v_lshlrev_b32_e32 v10, 16, v149
	v_and_b32_e32 v11, 0xffff0000, v149
	v_pk_mul_f32 v[12:13], v[68:69], v[60:61] op_sel_hi:[0,1]
	v_pk_mul_f32 v[14:15], v[68:69], v[62:63] op_sel_hi:[0,1]
	s_nop 0
	v_pk_mul_f32 v[2:3], v[158:159], v[14:15]
	v_pk_mul_f32 v[4:5], v[160:161], v[12:13]
	v_pk_mul_f32 v[2:3], v[2:3], v[8:9]
	v_pk_mul_f32 v[4:5], v[4:5], v[10:11]
	v_cvt_pk_bf16_f32 v2, v2, v3
	v_cvt_pk_bf16_f32 v3, v4, v5
	global_store_dwordx2 v[24:25], v[2:3], off offset:352
	s_nop 0
	v_pk_mul_f32 v[14:15], v[68:69], v[22:23] op_sel_hi:[0,1]
	s_nop 0
	v_lshlrev_b32_e32 v0, 16, v162
	v_and_b32_e32 v1, 0xffff0000, v162
	v_lshlrev_b32_e32 v6, 16, v163
	v_and_b32_e32 v7, 0xffff0000, v163
	s_nop 0
	v_pk_mul_f32 v[2:3], v[164:165], v[16:17]
	v_pk_mul_f32 v[4:5], v[166:167], v[14:15]
	v_pk_mul_f32 v[0:1], v[2:3], v[0:1]
	v_pk_mul_f32 v[4:5], v[4:5], v[6:7]
	v_cvt_pk_bf16_f32 v0, v0, v1
	v_cvt_pk_bf16_f32 v1, v4, v5
	global_store_dwordx2 v[24:25], v[0:1], off offset:384
	s_nop 0
	v_lshlrev_b32_e32 v4, 16, v168
	v_and_b32_e32 v5, 0xffff0000, v168
	v_lshlrev_b32_e32 v6, 16, v169
	v_and_b32_e32 v7, 0xffff0000, v169
	v_pk_mul_f32 v[8:9], v[68:69], v[54:55] op_sel_hi:[0,1]
	v_pk_mul_f32 v[14:15], v[68:69], v[52:53] op_sel_hi:[0,1]
	s_nop 0
	v_pk_mul_f32 v[0:1], v[174:175], v[14:15]
	v_pk_mul_f32 v[2:3], v[176:177], v[8:9]
	v_pk_mul_f32 v[0:1], v[0:1], v[4:5]
	v_pk_mul_f32 v[2:3], v[2:3], v[6:7]
	v_cvt_pk_bf16_f32 v0, v0, v1
	v_cvt_pk_bf16_f32 v1, v2, v3
	global_store_dwordx2 v[24:25], v[0:1], off offset:416
	v_lshlrev_b32_e32 v4, 16, v170
	v_and_b32_e32 v5, 0xffff0000, v170
	v_lshlrev_b32_e32 v6, 16, v171
	v_and_b32_e32 v7, 0xffff0000, v171
	v_pk_mul_f32 v[8:9], v[68:69], v[56:57] op_sel_hi:[0,1]
	v_pk_mul_f32 v[10:11], v[68:69], v[58:59] op_sel_hi:[0,1]
	s_nop 0
	v_pk_mul_f32 v[0:1], v[178:179], v[10:11]
	v_pk_mul_f32 v[2:3], v[180:181], v[8:9]
	v_pk_mul_f32 v[0:1], v[0:1], v[4:5]
	v_pk_mul_f32 v[2:3], v[2:3], v[6:7]
	v_cvt_pk_bf16_f32 v0, v0, v1
	v_cvt_pk_bf16_f32 v1, v2, v3
	global_store_dwordx2 v[24:25], v[0:1], off offset:448
	v_pk_mul_f32 v[8:9], v[68:69], v[48:49] op_sel_hi:[0,1]
	v_pk_mul_f32 v[10:11], v[68:69], v[50:51] op_sel_hi:[0,1]
	v_lshlrev_b32_e32 v4, 16, v172
	v_and_b32_e32 v5, 0xffff0000, v172
	v_lshlrev_b32_e32 v6, 16, v173
	v_and_b32_e32 v7, 0xffff0000, v173
	s_nop 0
	v_pk_mul_f32 v[0:1], v[182:183], v[10:11]
	v_pk_mul_f32 v[2:3], v[184:185], v[8:9]
	v_pk_mul_f32 v[0:1], v[0:1], v[4:5]
	v_pk_mul_f32 v[2:3], v[2:3], v[6:7]
	v_cvt_pk_bf16_f32 v0, v0, v1
	v_cvt_pk_bf16_f32 v1, v2, v3
	global_store_dwordx2 v[24:25], v[0:1], off offset:480

.LBB0_1413:
	v_lshl_add_u32 v238, s26, 8, v148
	v_lshlrev_b32_e32 v238, 11, v238
	v_bfe_u32 v239, v150, 2, 2
	v_and_b32_e32 v240, 1, v239
	v_lshrrev_b32_e32 v239, 1, v239
	v_lshlrev_b32_e32 v240, 4, v240
	v_lshl_add_u32 v240, v239, 3, v240
	v_and_b32_e32 v239, 0x60, v150
	v_add_u32_e32 v240, v240, v239
	v_lshl_add_u32 v240, s4, 8, v240
	v_add_lshl_u32 v238, v238, v240, 1
	v_mov_b32_e32 v240, v238
	v_add_u32_e32 v241, 0x10000, v238
	v_add_u32_e32 v242, 0x20000, v238
	v_add_u32_e32 v243, 0x30000, v238
	v_add_u32_e32 v244, 0x80000, v238
	v_add_u32_e32 v245, 0x90000, v238
	v_add_u32_e32 v246, 0xa0000, v238
	v_add_u32_e32 v247, 0xb0000, v238
	s_and_b64 vcc, exec, s[28:29]
	s_cbranch_vccnz .Lp6e_bz1
	global_load_dwordx4 v[154:157], v240, s[92:93] nt
	global_load_dwordx4 v[158:161], v240, s[92:93] offset:256 nt
	global_load_dwordx4 v[162:165], v241, s[92:93] nt
	global_load_dwordx4 v[166:169], v241, s[92:93] offset:256 nt
	global_load_dwordx4 v[170:173], v242, s[92:93] nt
	global_load_dwordx4 v[174:177], v242, s[92:93] offset:256 nt
	global_load_dwordx4 v[178:181], v243, s[92:93] nt
	global_load_dwordx4 v[182:185], v243, s[92:93] offset:256 nt
	global_load_dwordx4 v[190:193], v244, s[92:93] nt
	global_load_dwordx4 v[194:197], v244, s[92:93] offset:256 nt
	global_load_dwordx4 v[198:201], v245, s[92:93] nt
	global_load_dwordx4 v[202:205], v245, s[92:93] offset:256 nt
	global_load_dwordx4 v[206:209], v246, s[92:93] nt
	global_load_dwordx4 v[210:213], v246, s[92:93] offset:256 nt
	global_load_dwordx4 v[214:217], v247, s[92:93] nt
	global_load_dwordx4 v[230:233], v247, s[92:93] offset:256 nt
	s_waitcnt vmcnt(15)
	v_permlane16_swap_b32_e32 v154, v156
	v_permlane16_swap_b32_e32 v155, v157
	v_lshlrev_b32_e32 v136, 16, v154
	v_and_b32_e32 v137, 0xffff0000, v154
	v_lshlrev_b32_e32 v138, 16, v155
	v_and_b32_e32 v139, 0xffff0000, v155
	v_lshlrev_b32_e32 v140, 16, v156
	v_and_b32_e32 v141, 0xffff0000, v156
	v_lshlrev_b32_e32 v142, 16, v157
	v_and_b32_e32 v143, 0xffff0000, v157
	v_pk_mul_f32 v[124:125], v[124:125], v[136:137]
	v_pk_mul_f32 v[126:127], v[126:127], v[138:139]
	v_pk_mul_f32 v[120:121], v[120:121], v[140:141]
	v_pk_mul_f32 v[122:123], v[122:123], v[142:143]
	s_nop 0
	v_cvt_pk_bf16_f32 v124, v124, v125
	v_cvt_pk_bf16_f32 v125, v126, v127
	v_cvt_pk_bf16_f32 v126, v120, v121
	v_cvt_pk_bf16_f32 v127, v122, v123
	s_nop 1
	v_permlane16_swap_b32_e32 v124, v126
	v_permlane16_swap_b32_e32 v125, v127
	global_store_dwordx4 v240, v[124:127], s[64:65]
	s_waitcnt vmcnt(15)
	v_permlane16_swap_b32_e32 v158, v160
	v_permlane16_swap_b32_e32 v159, v161
	v_lshlrev_b32_e32 v136, 16, v158
	v_and_b32_e32 v137, 0xffff0000, v158
	v_lshlrev_b32_e32 v138, 16, v159
	v_and_b32_e32 v139, 0xffff0000, v159
	v_lshlrev_b32_e32 v140, 16, v160
	v_and_b32_e32 v141, 0xffff0000, v160
	v_lshlrev_b32_e32 v142, 16, v161
	v_and_b32_e32 v143, 0xffff0000, v161
	v_pk_mul_f32 v[116:117], v[116:117], v[136:137]
	v_pk_mul_f32 v[118:119], v[118:119], v[138:139]
	v_pk_mul_f32 v[112:113], v[112:113], v[140:141]
	v_pk_mul_f32 v[114:115], v[114:115], v[142:143]
	s_nop 0
	v_cvt_pk_bf16_f32 v116, v116, v117
	v_cvt_pk_bf16_f32 v117, v118, v119
	v_cvt_pk_bf16_f32 v118, v112, v113
	v_cvt_pk_bf16_f32 v119, v114, v115
	s_nop 1
	v_permlane16_swap_b32_e32 v116, v118
	v_permlane16_swap_b32_e32 v117, v119
	global_store_dwordx4 v240, v[116:119], s[64:65] offset:256
	s_waitcnt vmcnt(15)
	v_permlane16_swap_b32_e32 v162, v164
	v_permlane16_swap_b32_e32 v163, v165
	v_lshlrev_b32_e32 v136, 16, v162
	v_and_b32_e32 v137, 0xffff0000, v162
	v_lshlrev_b32_e32 v138, 16, v163
	v_and_b32_e32 v139, 0xffff0000, v163
	v_lshlrev_b32_e32 v140, 16, v164
	v_and_b32_e32 v141, 0xffff0000, v164
	v_lshlrev_b32_e32 v142, 16, v165
	v_and_b32_e32 v143, 0xffff0000, v165
	v_pk_mul_f32 v[108:109], v[108:109], v[136:137]
	v_pk_mul_f32 v[110:111], v[110:111], v[138:139]
	v_pk_mul_f32 v[104:105], v[104:105], v[140:141]
	v_pk_mul_f32 v[106:107], v[106:107], v[142:143]
	s_nop 0
	v_cvt_pk_bf16_f32 v108, v108, v109
	v_cvt_pk_bf16_f32 v109, v110, v111
	v_cvt_pk_bf16_f32 v110, v104, v105
	v_cvt_pk_bf16_f32 v111, v106, v107
	s_nop 1
	v_permlane16_swap_b32_e32 v108, v110
	v_permlane16_swap_b32_e32 v109, v111
	global_store_dwordx4 v241, v[108:111], s[64:65]
	s_waitcnt vmcnt(15)
	v_permlane16_swap_b32_e32 v166, v168
	v_permlane16_swap_b32_e32 v167, v169
	v_lshlrev_b32_e32 v136, 16, v166
	v_and_b32_e32 v137, 0xffff0000, v166
	v_lshlrev_b32_e32 v138, 16, v167
	v_and_b32_e32 v139, 0xffff0000, v167
	v_lshlrev_b32_e32 v140, 16, v168
	v_and_b32_e32 v141, 0xffff0000, v168
	v_lshlrev_b32_e32 v142, 16, v169
	v_and_b32_e32 v143, 0xffff0000, v169
	v_pk_mul_f32 v[100:101], v[100:101], v[136:137]
	v_pk_mul_f32 v[102:103], v[102:103], v[138:139]
	v_pk_mul_f32 v[96:97], v[96:97], v[140:141]
	v_pk_mul_f32 v[98:99], v[98:99], v[142:143]
	s_nop 0
	v_cvt_pk_bf16_f32 v100, v100, v101
	v_cvt_pk_bf16_f32 v101, v102, v103
	v_cvt_pk_bf16_f32 v102, v96, v97
	v_cvt_pk_bf16_f32 v103, v98, v99
	s_nop 1
	v_permlane16_swap_b32_e32 v100, v102
	v_permlane16_swap_b32_e32 v101, v103
	global_store_dwordx4 v241, v[100:103], s[64:65] offset:256
	s_waitcnt vmcnt(15)
	v_permlane16_swap_b32_e32 v170, v172
	v_permlane16_swap_b32_e32 v171, v173
	v_lshlrev_b32_e32 v136, 16, v170
	v_and_b32_e32 v137, 0xffff0000, v170
	v_lshlrev_b32_e32 v138, 16, v171
	v_and_b32_e32 v139, 0xffff0000, v171
	v_lshlrev_b32_e32 v140, 16, v172
	v_and_b32_e32 v141, 0xffff0000, v172
	v_lshlrev_b32_e32 v142, 16, v173
	v_and_b32_e32 v143, 0xffff0000, v173
	v_pk_mul_f32 v[92:93], v[92:93], v[136:137]
	v_pk_mul_f32 v[94:95], v[94:95], v[138:139]
	v_pk_mul_f32 v[88:89], v[88:89], v[140:141]
	v_pk_mul_f32 v[90:91], v[90:91], v[142:143]
	s_nop 0
	v_cvt_pk_bf16_f32 v92, v92, v93
	v_cvt_pk_bf16_f32 v93, v94, v95
	v_cvt_pk_bf16_f32 v94, v88, v89
	v_cvt_pk_bf16_f32 v95, v90, v91
	s_nop 1
	v_permlane16_swap_b32_e32 v92, v94
	v_permlane16_swap_b32_e32 v93, v95
	global_store_dwordx4 v242, v[92:95], s[64:65]
	s_waitcnt vmcnt(15)
	v_permlane16_swap_b32_e32 v174, v176
	v_permlane16_swap_b32_e32 v175, v177
	v_lshlrev_b32_e32 v136, 16, v174
	v_and_b32_e32 v137, 0xffff0000, v174
	v_lshlrev_b32_e32 v138, 16, v175
	v_and_b32_e32 v139, 0xffff0000, v175
	v_lshlrev_b32_e32 v140, 16, v176
	v_and_b32_e32 v141, 0xffff0000, v176
	v_lshlrev_b32_e32 v142, 16, v177
	v_and_b32_e32 v143, 0xffff0000, v177
	v_pk_mul_f32 v[84:85], v[84:85], v[136:137]
	v_pk_mul_f32 v[86:87], v[86:87], v[138:139]
	v_pk_mul_f32 v[80:81], v[80:81], v[140:141]
	v_pk_mul_f32 v[82:83], v[82:83], v[142:143]
	s_nop 0
	v_cvt_pk_bf16_f32 v84, v84, v85
	v_cvt_pk_bf16_f32 v85, v86, v87
	v_cvt_pk_bf16_f32 v86, v80, v81
	v_cvt_pk_bf16_f32 v87, v82, v83
	s_nop 1
	v_permlane16_swap_b32_e32 v84, v86
	v_permlane16_swap_b32_e32 v85, v87
	global_store_dwordx4 v242, v[84:87], s[64:65] offset:256
	s_waitcnt vmcnt(15)
	v_permlane16_swap_b32_e32 v178, v180
	v_permlane16_swap_b32_e32 v179, v181
	v_lshlrev_b32_e32 v136, 16, v178
	v_and_b32_e32 v137, 0xffff0000, v178
	v_lshlrev_b32_e32 v138, 16, v179
	v_and_b32_e32 v139, 0xffff0000, v179
	v_lshlrev_b32_e32 v140, 16, v180
	v_and_b32_e32 v141, 0xffff0000, v180
	v_lshlrev_b32_e32 v142, 16, v181
	v_and_b32_e32 v143, 0xffff0000, v181
	v_pk_mul_f32 v[76:77], v[76:77], v[136:137]
	v_pk_mul_f32 v[78:79], v[78:79], v[138:139]
	v_pk_mul_f32 v[72:73], v[72:73], v[140:141]
	v_pk_mul_f32 v[74:75], v[74:75], v[142:143]
	s_nop 0
	v_cvt_pk_bf16_f32 v76, v76, v77
	v_cvt_pk_bf16_f32 v77, v78, v79
	v_cvt_pk_bf16_f32 v78, v72, v73
	v_cvt_pk_bf16_f32 v79, v74, v75
	s_nop 1
	v_permlane16_swap_b32_e32 v76, v78
	v_permlane16_swap_b32_e32 v77, v79
	global_store_dwordx4 v243, v[76:79], s[64:65]
	s_waitcnt vmcnt(15)
	v_permlane16_swap_b32_e32 v182, v184
	v_permlane16_swap_b32_e32 v183, v185
	v_lshlrev_b32_e32 v136, 16, v182
	v_and_b32_e32 v137, 0xffff0000, v182
	v_lshlrev_b32_e32 v138, 16, v183
	v_and_b32_e32 v139, 0xffff0000, v183
	v_lshlrev_b32_e32 v140, 16, v184
	v_and_b32_e32 v141, 0xffff0000, v184
	v_lshlrev_b32_e32 v142, 16, v185
	v_and_b32_e32 v143, 0xffff0000, v185
	v_pk_mul_f32 v[68:69], v[68:69], v[136:137]
	v_pk_mul_f32 v[70:71], v[70:71], v[138:139]
	v_pk_mul_f32 v[64:65], v[64:65], v[140:141]
	v_pk_mul_f32 v[66:67], v[66:67], v[142:143]
	s_nop 0
	v_cvt_pk_bf16_f32 v68, v68, v69
	v_cvt_pk_bf16_f32 v69, v70, v71
	v_cvt_pk_bf16_f32 v70, v64, v65
	v_cvt_pk_bf16_f32 v71, v66, v67
	s_nop 1
	v_permlane16_swap_b32_e32 v68, v70
	v_permlane16_swap_b32_e32 v69, v71
	global_store_dwordx4 v243, v[68:71], s[64:65] offset:256
	s_waitcnt vmcnt(15)
	v_permlane16_swap_b32_e32 v190, v192
	v_permlane16_swap_b32_e32 v191, v193
	v_lshlrev_b32_e32 v136, 16, v190
	v_and_b32_e32 v137, 0xffff0000, v190
	v_lshlrev_b32_e32 v138, 16, v191
	v_and_b32_e32 v139, 0xffff0000, v191
	v_lshlrev_b32_e32 v140, 16, v192
	v_and_b32_e32 v141, 0xffff0000, v192
	v_lshlrev_b32_e32 v142, 16, v193
	v_and_b32_e32 v143, 0xffff0000, v193
	v_pk_mul_f32 v[60:61], v[60:61], v[136:137]
	v_pk_mul_f32 v[62:63], v[62:63], v[138:139]
	v_pk_mul_f32 v[56:57], v[56:57], v[140:141]
	v_pk_mul_f32 v[58:59], v[58:59], v[142:143]
	s_nop 0
	v_cvt_pk_bf16_f32 v60, v60, v61
	v_cvt_pk_bf16_f32 v61, v62, v63
	v_cvt_pk_bf16_f32 v62, v56, v57
	v_cvt_pk_bf16_f32 v63, v58, v59
	s_nop 1
	v_permlane16_swap_b32_e32 v60, v62
	v_permlane16_swap_b32_e32 v61, v63
	global_store_dwordx4 v244, v[60:63], s[64:65]
	s_waitcnt vmcnt(15)
	v_permlane16_swap_b32_e32 v194, v196
	v_permlane16_swap_b32_e32 v195, v197
	v_lshlrev_b32_e32 v136, 16, v194
	v_and_b32_e32 v137, 0xffff0000, v194
	v_lshlrev_b32_e32 v138, 16, v195
	v_and_b32_e32 v139, 0xffff0000, v195
	v_lshlrev_b32_e32 v140, 16, v196
	v_and_b32_e32 v141, 0xffff0000, v196
	v_lshlrev_b32_e32 v142, 16, v197
	v_and_b32_e32 v143, 0xffff0000, v197
	v_pk_mul_f32 v[52:53], v[52:53], v[136:137]
	v_pk_mul_f32 v[54:55], v[54:55], v[138:139]
	v_pk_mul_f32 v[48:49], v[48:49], v[140:141]
	v_pk_mul_f32 v[50:51], v[50:51], v[142:143]
	s_nop 0
	v_cvt_pk_bf16_f32 v52, v52, v53
	v_cvt_pk_bf16_f32 v53, v54, v55
	v_cvt_pk_bf16_f32 v54, v48, v49
	v_cvt_pk_bf16_f32 v55, v50, v51
	s_nop 1
	v_permlane16_swap_b32_e32 v52, v54
	v_permlane16_swap_b32_e32 v53, v55
	global_store_dwordx4 v244, v[52:55], s[64:65] offset:256
	s_waitcnt vmcnt(15)
	v_permlane16_swap_b32_e32 v198, v200
	v_permlane16_swap_b32_e32 v199, v201
	v_lshlrev_b32_e32 v136, 16, v198
	v_and_b32_e32 v137, 0xffff0000, v198
	v_lshlrev_b32_e32 v138, 16, v199
	v_and_b32_e32 v139, 0xffff0000, v199
	v_lshlrev_b32_e32 v140, 16, v200
	v_and_b32_e32 v141, 0xffff0000, v200
	v_lshlrev_b32_e32 v142, 16, v201
	v_and_b32_e32 v143, 0xffff0000, v201
	v_pk_mul_f32 v[44:45], v[44:45], v[136:137]
	v_pk_mul_f32 v[46:47], v[46:47], v[138:139]
	v_pk_mul_f32 v[40:41], v[40:41], v[140:141]
	v_pk_mul_f32 v[42:43], v[42:43], v[142:143]
	s_nop 0
	v_cvt_pk_bf16_f32 v44, v44, v45
	v_cvt_pk_bf16_f32 v45, v46, v47
	v_cvt_pk_bf16_f32 v46, v40, v41
	v_cvt_pk_bf16_f32 v47, v42, v43
	s_nop 1
	v_permlane16_swap_b32_e32 v44, v46
	v_permlane16_swap_b32_e32 v45, v47
	global_store_dwordx4 v245, v[44:47], s[64:65]
	s_waitcnt vmcnt(15)
	v_permlane16_swap_b32_e32 v202, v204
	v_permlane16_swap_b32_e32 v203, v205
	v_lshlrev_b32_e32 v136, 16, v202
	v_and_b32_e32 v137, 0xffff0000, v202
	v_lshlrev_b32_e32 v138, 16, v203
	v_and_b32_e32 v139, 0xffff0000, v203
	v_lshlrev_b32_e32 v140, 16, v204
	v_and_b32_e32 v141, 0xffff0000, v204
	v_lshlrev_b32_e32 v142, 16, v205
	v_and_b32_e32 v143, 0xffff0000, v205
	v_pk_mul_f32 v[36:37], v[36:37], v[136:137]
	v_pk_mul_f32 v[38:39], v[38:39], v[138:139]
	v_pk_mul_f32 v[32:33], v[32:33], v[140:141]
	v_pk_mul_f32 v[34:35], v[34:35], v[142:143]
	s_nop 0
	v_cvt_pk_bf16_f32 v36, v36, v37
	v_cvt_pk_bf16_f32 v37, v38, v39
	v_cvt_pk_bf16_f32 v38, v32, v33
	v_cvt_pk_bf16_f32 v39, v34, v35
	s_nop 1
	v_permlane16_swap_b32_e32 v36, v38
	v_permlane16_swap_b32_e32 v37, v39
	global_store_dwordx4 v245, v[36:39], s[64:65] offset:256
	s_waitcnt vmcnt(15)
	v_permlane16_swap_b32_e32 v206, v208
	v_permlane16_swap_b32_e32 v207, v209
	v_lshlrev_b32_e32 v136, 16, v206
	v_and_b32_e32 v137, 0xffff0000, v206
	v_lshlrev_b32_e32 v138, 16, v207
	v_and_b32_e32 v139, 0xffff0000, v207
	v_lshlrev_b32_e32 v140, 16, v208
	v_and_b32_e32 v141, 0xffff0000, v208
	v_lshlrev_b32_e32 v142, 16, v209
	v_and_b32_e32 v143, 0xffff0000, v209
	v_pk_mul_f32 v[28:29], v[28:29], v[136:137]
	v_pk_mul_f32 v[30:31], v[30:31], v[138:139]
	v_pk_mul_f32 v[24:25], v[24:25], v[140:141]
	v_pk_mul_f32 v[26:27], v[26:27], v[142:143]
	s_nop 0
	v_cvt_pk_bf16_f32 v28, v28, v29
	v_cvt_pk_bf16_f32 v29, v30, v31
	v_cvt_pk_bf16_f32 v30, v24, v25
	v_cvt_pk_bf16_f32 v31, v26, v27
	s_nop 1
	v_permlane16_swap_b32_e32 v28, v30
	v_permlane16_swap_b32_e32 v29, v31
	global_store_dwordx4 v246, v[28:31], s[64:65]
	s_waitcnt vmcnt(15)
	v_permlane16_swap_b32_e32 v210, v212
	v_permlane16_swap_b32_e32 v211, v213
	v_lshlrev_b32_e32 v136, 16, v210
	v_and_b32_e32 v137, 0xffff0000, v210
	v_lshlrev_b32_e32 v138, 16, v211
	v_and_b32_e32 v139, 0xffff0000, v211
	v_lshlrev_b32_e32 v140, 16, v212
	v_and_b32_e32 v141, 0xffff0000, v212
	v_lshlrev_b32_e32 v142, 16, v213
	v_and_b32_e32 v143, 0xffff0000, v213
	v_pk_mul_f32 v[20:21], v[20:21], v[136:137]
	v_pk_mul_f32 v[22:23], v[22:23], v[138:139]
	v_pk_mul_f32 v[16:17], v[16:17], v[140:141]
	v_pk_mul_f32 v[18:19], v[18:19], v[142:143]
	s_nop 0
	v_cvt_pk_bf16_f32 v20, v20, v21
	v_cvt_pk_bf16_f32 v21, v22, v23
	v_cvt_pk_bf16_f32 v22, v16, v17
	v_cvt_pk_bf16_f32 v23, v18, v19
	s_nop 1
	v_permlane16_swap_b32_e32 v20, v22
	v_permlane16_swap_b32_e32 v21, v23
	global_store_dwordx4 v246, v[20:23], s[64:65] offset:256
	s_waitcnt vmcnt(15)
	v_permlane16_swap_b32_e32 v214, v216
	v_permlane16_swap_b32_e32 v215, v217
	v_lshlrev_b32_e32 v136, 16, v214
	v_and_b32_e32 v137, 0xffff0000, v214
	v_lshlrev_b32_e32 v138, 16, v215
	v_and_b32_e32 v139, 0xffff0000, v215
	v_lshlrev_b32_e32 v140, 16, v216
	v_and_b32_e32 v141, 0xffff0000, v216
	v_lshlrev_b32_e32 v142, 16, v217
	v_and_b32_e32 v143, 0xffff0000, v217
	v_pk_mul_f32 v[12:13], v[12:13], v[136:137]
	v_pk_mul_f32 v[14:15], v[14:15], v[138:139]
	v_pk_mul_f32 v[8:9], v[8:9], v[140:141]
	v_pk_mul_f32 v[10:11], v[10:11], v[142:143]
	s_nop 0
	v_cvt_pk_bf16_f32 v12, v12, v13
	v_cvt_pk_bf16_f32 v13, v14, v15
	v_cvt_pk_bf16_f32 v14, v8, v9
	v_cvt_pk_bf16_f32 v15, v10, v11
	s_nop 1
	v_permlane16_swap_b32_e32 v12, v14
	v_permlane16_swap_b32_e32 v13, v15
	global_store_dwordx4 v247, v[12:15], s[64:65]
	s_waitcnt vmcnt(15)
	v_permlane16_swap_b32_e32 v230, v232
	v_permlane16_swap_b32_e32 v231, v233
	v_lshlrev_b32_e32 v136, 16, v230
	v_and_b32_e32 v137, 0xffff0000, v230
	v_lshlrev_b32_e32 v138, 16, v231
	v_and_b32_e32 v139, 0xffff0000, v231
	v_lshlrev_b32_e32 v140, 16, v232
	v_and_b32_e32 v141, 0xffff0000, v232
	v_lshlrev_b32_e32 v142, 16, v233
	v_and_b32_e32 v143, 0xffff0000, v233
	v_pk_mul_f32 v[4:5], v[4:5], v[136:137]
	v_pk_mul_f32 v[6:7], v[6:7], v[138:139]
	v_pk_mul_f32 v[0:1], v[0:1], v[140:141]
	v_pk_mul_f32 v[2:3], v[2:3], v[142:143]
	s_nop 0
	v_cvt_pk_bf16_f32 v4, v4, v5
	v_cvt_pk_bf16_f32 v5, v6, v7
	v_cvt_pk_bf16_f32 v6, v0, v1
	v_cvt_pk_bf16_f32 v7, v2, v3
	s_nop 1
	v_permlane16_swap_b32_e32 v4, v6
	v_permlane16_swap_b32_e32 v5, v7
	global_store_dwordx4 v247, v[4:7], s[64:65] offset:256
	s_branch .Lp6e_done
.Lp6e_bz1:
	global_load_dwordx4 v[154:157], v240, s[64:65] nt
	global_load_dwordx4 v[190:193], v240, s[94:95] nt
	global_load_dwordx4 v[158:161], v240, s[64:65] offset:256 nt
	global_load_dwordx4 v[194:197], v240, s[94:95] offset:256 nt
	global_load_dwordx4 v[162:165], v241, s[64:65] nt
	global_load_dwordx4 v[198:201], v241, s[94:95] nt
	global_load_dwordx4 v[166:169], v241, s[64:65] offset:256 nt
	global_load_dwordx4 v[202:205], v241, s[94:95] offset:256 nt
	global_load_dwordx4 v[170:173], v242, s[64:65] nt
	global_load_dwordx4 v[206:209], v242, s[94:95] nt
	global_load_dwordx4 v[174:177], v242, s[64:65] offset:256 nt
	global_load_dwordx4 v[210:213], v242, s[94:95] offset:256 nt
	global_load_dwordx4 v[178:181], v243, s[64:65] nt
	global_load_dwordx4 v[214:217], v243, s[94:95] nt
	global_load_dwordx4 v[182:185], v243, s[64:65] offset:256 nt
	global_load_dwordx4 v[230:233], v243, s[94:95] offset:256 nt
	s_waitcnt vmcnt(14)
	v_permlane16_swap_b32_e32 v154, v156
	v_permlane16_swap_b32_e32 v155, v157
	v_permlane16_swap_b32_e32 v190, v192
	v_permlane16_swap_b32_e32 v191, v193
	v_lshlrev_b32_e32 v136, 16, v154
	v_and_b32_e32 v137, 0xffff0000, v154
	v_lshlrev_b32_e32 v138, 16, v155
	v_and_b32_e32 v139, 0xffff0000, v155
	v_lshlrev_b32_e32 v140, 16, v156
	v_and_b32_e32 v141, 0xffff0000, v156
	v_lshlrev_b32_e32 v142, 16, v157
	v_and_b32_e32 v143, 0xffff0000, v157
	v_lshlrev_b32_e32 v144, 16, v190
	v_and_b32_e32 v145, 0xffff0000, v190
	v_lshlrev_b32_e32 v146, 16, v191
	v_and_b32_e32 v147, 0xffff0000, v191
	v_lshlrev_b32_e32 v234, 16, v192
	v_and_b32_e32 v235, 0xffff0000, v192
	v_lshlrev_b32_e32 v236, 16, v193
	v_and_b32_e32 v237, 0xffff0000, v193
	global_load_dwordx4 v[154:157], v244, s[64:65] nt
	global_load_dwordx4 v[190:193], v244, s[94:95] nt
	v_pk_fma_f32 v[124:125], v[124:125], v[144:145], v[136:137]
	v_pk_fma_f32 v[126:127], v[126:127], v[146:147], v[138:139]
	v_pk_fma_f32 v[120:121], v[120:121], v[234:235], v[140:141]
	v_pk_fma_f32 v[122:123], v[122:123], v[236:237], v[142:143]
	s_nop 0
	v_cvt_pk_bf16_f32 v124, v124, v125
	v_cvt_pk_bf16_f32 v125, v126, v127
	v_cvt_pk_bf16_f32 v126, v120, v121
	v_cvt_pk_bf16_f32 v127, v122, v123
	s_nop 1
	v_permlane16_swap_b32_e32 v124, v126
	v_permlane16_swap_b32_e32 v125, v127
	global_store_dwordx4 v240, v[124:127], s[90:91]
	s_waitcnt vmcnt(15)
	v_permlane16_swap_b32_e32 v158, v160
	v_permlane16_swap_b32_e32 v159, v161
	v_permlane16_swap_b32_e32 v194, v196
	v_permlane16_swap_b32_e32 v195, v197
	v_lshlrev_b32_e32 v136, 16, v158
	v_and_b32_e32 v137, 0xffff0000, v158
	v_lshlrev_b32_e32 v138, 16, v159
	v_and_b32_e32 v139, 0xffff0000, v159
	v_lshlrev_b32_e32 v140, 16, v160
	v_and_b32_e32 v141, 0xffff0000, v160
	v_lshlrev_b32_e32 v142, 16, v161
	v_and_b32_e32 v143, 0xffff0000, v161
	v_lshlrev_b32_e32 v144, 16, v194
	v_and_b32_e32 v145, 0xffff0000, v194
	v_lshlrev_b32_e32 v146, 16, v195
	v_and_b32_e32 v147, 0xffff0000, v195
	v_lshlrev_b32_e32 v234, 16, v196
	v_and_b32_e32 v235, 0xffff0000, v196
	v_lshlrev_b32_e32 v236, 16, v197
	v_and_b32_e32 v237, 0xffff0000, v197
	global_load_dwordx4 v[158:161], v244, s[64:65] offset:256 nt
	global_load_dwordx4 v[194:197], v244, s[94:95] offset:256 nt
	v_pk_fma_f32 v[116:117], v[116:117], v[144:145], v[136:137]
	v_pk_fma_f32 v[118:119], v[118:119], v[146:147], v[138:139]
	v_pk_fma_f32 v[112:113], v[112:113], v[234:235], v[140:141]
	v_pk_fma_f32 v[114:115], v[114:115], v[236:237], v[142:143]
	s_nop 0
	v_cvt_pk_bf16_f32 v116, v116, v117
	v_cvt_pk_bf16_f32 v117, v118, v119
	v_cvt_pk_bf16_f32 v118, v112, v113
	v_cvt_pk_bf16_f32 v119, v114, v115
	s_nop 1
	v_permlane16_swap_b32_e32 v116, v118
	v_permlane16_swap_b32_e32 v117, v119
	global_store_dwordx4 v240, v[116:119], s[90:91] offset:256
	s_waitcnt vmcnt(16)
	v_permlane16_swap_b32_e32 v162, v164
	v_permlane16_swap_b32_e32 v163, v165
	v_permlane16_swap_b32_e32 v198, v200
	v_permlane16_swap_b32_e32 v199, v201
	v_lshlrev_b32_e32 v136, 16, v162
	v_and_b32_e32 v137, 0xffff0000, v162
	v_lshlrev_b32_e32 v138, 16, v163
	v_and_b32_e32 v139, 0xffff0000, v163
	v_lshlrev_b32_e32 v140, 16, v164
	v_and_b32_e32 v141, 0xffff0000, v164
	v_lshlrev_b32_e32 v142, 16, v165
	v_and_b32_e32 v143, 0xffff0000, v165
	v_lshlrev_b32_e32 v144, 16, v198
	v_and_b32_e32 v145, 0xffff0000, v198
	v_lshlrev_b32_e32 v146, 16, v199
	v_and_b32_e32 v147, 0xffff0000, v199
	v_lshlrev_b32_e32 v234, 16, v200
	v_and_b32_e32 v235, 0xffff0000, v200
	v_lshlrev_b32_e32 v236, 16, v201
	v_and_b32_e32 v237, 0xffff0000, v201
	global_load_dwordx4 v[162:165], v245, s[64:65] nt
	global_load_dwordx4 v[198:201], v245, s[94:95] nt
	v_pk_fma_f32 v[108:109], v[108:109], v[144:145], v[136:137]
	v_pk_fma_f32 v[110:111], v[110:111], v[146:147], v[138:139]
	v_pk_fma_f32 v[104:105], v[104:105], v[234:235], v[140:141]
	v_pk_fma_f32 v[106:107], v[106:107], v[236:237], v[142:143]
	s_nop 0
	v_cvt_pk_bf16_f32 v108, v108, v109
	v_cvt_pk_bf16_f32 v109, v110, v111
	v_cvt_pk_bf16_f32 v110, v104, v105
	v_cvt_pk_bf16_f32 v111, v106, v107
	s_nop 1
	v_permlane16_swap_b32_e32 v108, v110
	v_permlane16_swap_b32_e32 v109, v111
	global_store_dwordx4 v241, v[108:111], s[90:91]
	s_waitcnt vmcnt(17)
	v_permlane16_swap_b32_e32 v166, v168
	v_permlane16_swap_b32_e32 v167, v169
	v_permlane16_swap_b32_e32 v202, v204
	v_permlane16_swap_b32_e32 v203, v205
	v_lshlrev_b32_e32 v136, 16, v166
	v_and_b32_e32 v137, 0xffff0000, v166
	v_lshlrev_b32_e32 v138, 16, v167
	v_and_b32_e32 v139, 0xffff0000, v167
	v_lshlrev_b32_e32 v140, 16, v168
	v_and_b32_e32 v141, 0xffff0000, v168
	v_lshlrev_b32_e32 v142, 16, v169
	v_and_b32_e32 v143, 0xffff0000, v169
	v_lshlrev_b32_e32 v144, 16, v202
	v_and_b32_e32 v145, 0xffff0000, v202
	v_lshlrev_b32_e32 v146, 16, v203
	v_and_b32_e32 v147, 0xffff0000, v203
	v_lshlrev_b32_e32 v234, 16, v204
	v_and_b32_e32 v235, 0xffff0000, v204
	v_lshlrev_b32_e32 v236, 16, v205
	v_and_b32_e32 v237, 0xffff0000, v205
	global_load_dwordx4 v[166:169], v245, s[64:65] offset:256 nt
	global_load_dwordx4 v[202:205], v245, s[94:95] offset:256 nt
	v_pk_fma_f32 v[100:101], v[100:101], v[144:145], v[136:137]
	v_pk_fma_f32 v[102:103], v[102:103], v[146:147], v[138:139]
	v_pk_fma_f32 v[96:97], v[96:97], v[234:235], v[140:141]
	v_pk_fma_f32 v[98:99], v[98:99], v[236:237], v[142:143]
	s_nop 0
	v_cvt_pk_bf16_f32 v100, v100, v101
	v_cvt_pk_bf16_f32 v101, v102, v103
	v_cvt_pk_bf16_f32 v102, v96, v97
	v_cvt_pk_bf16_f32 v103, v98, v99
	s_nop 1
	v_permlane16_swap_b32_e32 v100, v102
	v_permlane16_swap_b32_e32 v101, v103
	global_store_dwordx4 v241, v[100:103], s[90:91] offset:256
	s_waitcnt vmcnt(18)
	v_permlane16_swap_b32_e32 v170, v172
	v_permlane16_swap_b32_e32 v171, v173
	v_permlane16_swap_b32_e32 v206, v208
	v_permlane16_swap_b32_e32 v207, v209
	v_lshlrev_b32_e32 v136, 16, v170
	v_and_b32_e32 v137, 0xffff0000, v170
	v_lshlrev_b32_e32 v138, 16, v171
	v_and_b32_e32 v139, 0xffff0000, v171
	v_lshlrev_b32_e32 v140, 16, v172
	v_and_b32_e32 v141, 0xffff0000, v172
	v_lshlrev_b32_e32 v142, 16, v173
	v_and_b32_e32 v143, 0xffff0000, v173
	v_lshlrev_b32_e32 v144, 16, v206
	v_and_b32_e32 v145, 0xffff0000, v206
	v_lshlrev_b32_e32 v146, 16, v207
	v_and_b32_e32 v147, 0xffff0000, v207
	v_lshlrev_b32_e32 v234, 16, v208
	v_and_b32_e32 v235, 0xffff0000, v208
	v_lshlrev_b32_e32 v236, 16, v209
	v_and_b32_e32 v237, 0xffff0000, v209
	global_load_dwordx4 v[170:173], v246, s[64:65] nt
	global_load_dwordx4 v[206:209], v246, s[94:95] nt
	v_pk_fma_f32 v[92:93], v[92:93], v[144:145], v[136:137]
	v_pk_fma_f32 v[94:95], v[94:95], v[146:147], v[138:139]
	v_pk_fma_f32 v[88:89], v[88:89], v[234:235], v[140:141]
	v_pk_fma_f32 v[90:91], v[90:91], v[236:237], v[142:143]
	s_nop 0
	v_cvt_pk_bf16_f32 v92, v92, v93
	v_cvt_pk_bf16_f32 v93, v94, v95
	v_cvt_pk_bf16_f32 v94, v88, v89
	v_cvt_pk_bf16_f32 v95, v90, v91
	s_nop 1
	v_permlane16_swap_b32_e32 v92, v94
	v_permlane16_swap_b32_e32 v93, v95
	global_store_dwordx4 v242, v[92:95], s[90:91]
	s_waitcnt vmcnt(19)
	v_permlane16_swap_b32_e32 v174, v176
	v_permlane16_swap_b32_e32 v175, v177
	v_permlane16_swap_b32_e32 v210, v212
	v_permlane16_swap_b32_e32 v211, v213
	v_lshlrev_b32_e32 v136, 16, v174
	v_and_b32_e32 v137, 0xffff0000, v174
	v_lshlrev_b32_e32 v138, 16, v175
	v_and_b32_e32 v139, 0xffff0000, v175
	v_lshlrev_b32_e32 v140, 16, v176
	v_and_b32_e32 v141, 0xffff0000, v176
	v_lshlrev_b32_e32 v142, 16, v177
	v_and_b32_e32 v143, 0xffff0000, v177
	v_lshlrev_b32_e32 v144, 16, v210
	v_and_b32_e32 v145, 0xffff0000, v210
	v_lshlrev_b32_e32 v146, 16, v211
	v_and_b32_e32 v147, 0xffff0000, v211
	v_lshlrev_b32_e32 v234, 16, v212
	v_and_b32_e32 v235, 0xffff0000, v212
	v_lshlrev_b32_e32 v236, 16, v213
	v_and_b32_e32 v237, 0xffff0000, v213
	global_load_dwordx4 v[174:177], v246, s[64:65] offset:256 nt
	global_load_dwordx4 v[210:213], v246, s[94:95] offset:256 nt
	v_pk_fma_f32 v[84:85], v[84:85], v[144:145], v[136:137]
	v_pk_fma_f32 v[86:87], v[86:87], v[146:147], v[138:139]
	v_pk_fma_f32 v[80:81], v[80:81], v[234:235], v[140:141]
	v_pk_fma_f32 v[82:83], v[82:83], v[236:237], v[142:143]
	s_nop 0
	v_cvt_pk_bf16_f32 v84, v84, v85
	v_cvt_pk_bf16_f32 v85, v86, v87
	v_cvt_pk_bf16_f32 v86, v80, v81
	v_cvt_pk_bf16_f32 v87, v82, v83
	s_nop 1
	v_permlane16_swap_b32_e32 v84, v86
	v_permlane16_swap_b32_e32 v85, v87
	global_store_dwordx4 v242, v[84:87], s[90:91] offset:256
	s_waitcnt vmcnt(20)
	v_permlane16_swap_b32_e32 v178, v180
	v_permlane16_swap_b32_e32 v179, v181
	v_permlane16_swap_b32_e32 v214, v216
	v_permlane16_swap_b32_e32 v215, v217
	v_lshlrev_b32_e32 v136, 16, v178
	v_and_b32_e32 v137, 0xffff0000, v178
	v_lshlrev_b32_e32 v138, 16, v179
	v_and_b32_e32 v139, 0xffff0000, v179
	v_lshlrev_b32_e32 v140, 16, v180
	v_and_b32_e32 v141, 0xffff0000, v180
	v_lshlrev_b32_e32 v142, 16, v181
	v_and_b32_e32 v143, 0xffff0000, v181
	v_lshlrev_b32_e32 v144, 16, v214
	v_and_b32_e32 v145, 0xffff0000, v214
	v_lshlrev_b32_e32 v146, 16, v215
	v_and_b32_e32 v147, 0xffff0000, v215
	v_lshlrev_b32_e32 v234, 16, v216
	v_and_b32_e32 v235, 0xffff0000, v216
	v_lshlrev_b32_e32 v236, 16, v217
	v_and_b32_e32 v237, 0xffff0000, v217
	global_load_dwordx4 v[178:181], v247, s[64:65] nt
	global_load_dwordx4 v[214:217], v247, s[94:95] nt
	v_pk_fma_f32 v[76:77], v[76:77], v[144:145], v[136:137]
	v_pk_fma_f32 v[78:79], v[78:79], v[146:147], v[138:139]
	v_pk_fma_f32 v[72:73], v[72:73], v[234:235], v[140:141]
	v_pk_fma_f32 v[74:75], v[74:75], v[236:237], v[142:143]
	s_nop 0
	v_cvt_pk_bf16_f32 v76, v76, v77
	v_cvt_pk_bf16_f32 v77, v78, v79
	v_cvt_pk_bf16_f32 v78, v72, v73
	v_cvt_pk_bf16_f32 v79, v74, v75
	s_nop 1
	v_permlane16_swap_b32_e32 v76, v78
	v_permlane16_swap_b32_e32 v77, v79
	global_store_dwordx4 v243, v[76:79], s[90:91]
	s_waitcnt vmcnt(21)
	v_permlane16_swap_b32_e32 v182, v184
	v_permlane16_swap_b32_e32 v183, v185
	v_permlane16_swap_b32_e32 v230, v232
	v_permlane16_swap_b32_e32 v231, v233
	v_lshlrev_b32_e32 v136, 16, v182
	v_and_b32_e32 v137, 0xffff0000, v182
	v_lshlrev_b32_e32 v138, 16, v183
	v_and_b32_e32 v139, 0xffff0000, v183
	v_lshlrev_b32_e32 v140, 16, v184
	v_and_b32_e32 v141, 0xffff0000, v184
	v_lshlrev_b32_e32 v142, 16, v185
	v_and_b32_e32 v143, 0xffff0000, v185
	v_lshlrev_b32_e32 v144, 16, v230
	v_and_b32_e32 v145, 0xffff0000, v230
	v_lshlrev_b32_e32 v146, 16, v231
	v_and_b32_e32 v147, 0xffff0000, v231
	v_lshlrev_b32_e32 v234, 16, v232
	v_and_b32_e32 v235, 0xffff0000, v232
	v_lshlrev_b32_e32 v236, 16, v233
	v_and_b32_e32 v237, 0xffff0000, v233
	global_load_dwordx4 v[182:185], v247, s[64:65] offset:256 nt
	global_load_dwordx4 v[230:233], v247, s[94:95] offset:256 nt
	v_pk_fma_f32 v[68:69], v[68:69], v[144:145], v[136:137]
	v_pk_fma_f32 v[70:71], v[70:71], v[146:147], v[138:139]
	v_pk_fma_f32 v[64:65], v[64:65], v[234:235], v[140:141]
	v_pk_fma_f32 v[66:67], v[66:67], v[236:237], v[142:143]
	s_nop 0
	v_cvt_pk_bf16_f32 v68, v68, v69
	v_cvt_pk_bf16_f32 v69, v70, v71
	v_cvt_pk_bf16_f32 v70, v64, v65
	v_cvt_pk_bf16_f32 v71, v66, v67
	s_nop 1
	v_permlane16_swap_b32_e32 v68, v70
	v_permlane16_swap_b32_e32 v69, v71
	global_store_dwordx4 v243, v[68:71], s[90:91] offset:256
	s_waitcnt vmcnt(22)
	v_permlane16_swap_b32_e32 v154, v156
	v_permlane16_swap_b32_e32 v155, v157
	v_permlane16_swap_b32_e32 v190, v192
	v_permlane16_swap_b32_e32 v191, v193
	v_lshlrev_b32_e32 v136, 16, v154
	v_and_b32_e32 v137, 0xffff0000, v154
	v_lshlrev_b32_e32 v138, 16, v155
	v_and_b32_e32 v139, 0xffff0000, v155
	v_lshlrev_b32_e32 v140, 16, v156
	v_and_b32_e32 v141, 0xffff0000, v156
	v_lshlrev_b32_e32 v142, 16, v157
	v_and_b32_e32 v143, 0xffff0000, v157
	v_lshlrev_b32_e32 v144, 16, v190
	v_and_b32_e32 v145, 0xffff0000, v190
	v_lshlrev_b32_e32 v146, 16, v191
	v_and_b32_e32 v147, 0xffff0000, v191
	v_lshlrev_b32_e32 v234, 16, v192
	v_and_b32_e32 v235, 0xffff0000, v192
	v_lshlrev_b32_e32 v236, 16, v193
	v_and_b32_e32 v237, 0xffff0000, v193
	v_pk_fma_f32 v[60:61], v[60:61], v[144:145], v[136:137]
	v_pk_fma_f32 v[62:63], v[62:63], v[146:147], v[138:139]
	v_pk_fma_f32 v[56:57], v[56:57], v[234:235], v[140:141]
	v_pk_fma_f32 v[58:59], v[58:59], v[236:237], v[142:143]
	s_nop 0
	v_cvt_pk_bf16_f32 v60, v60, v61
	v_cvt_pk_bf16_f32 v61, v62, v63
	v_cvt_pk_bf16_f32 v62, v56, v57
	v_cvt_pk_bf16_f32 v63, v58, v59
	s_nop 1
	v_permlane16_swap_b32_e32 v60, v62
	v_permlane16_swap_b32_e32 v61, v63
	global_store_dwordx4 v244, v[60:63], s[90:91]
	s_waitcnt vmcnt(20)
	v_permlane16_swap_b32_e32 v158, v160
	v_permlane16_swap_b32_e32 v159, v161
	v_permlane16_swap_b32_e32 v194, v196
	v_permlane16_swap_b32_e32 v195, v197
	v_lshlrev_b32_e32 v136, 16, v158
	v_and_b32_e32 v137, 0xffff0000, v158
	v_lshlrev_b32_e32 v138, 16, v159
	v_and_b32_e32 v139, 0xffff0000, v159
	v_lshlrev_b32_e32 v140, 16, v160
	v_and_b32_e32 v141, 0xffff0000, v160
	v_lshlrev_b32_e32 v142, 16, v161
	v_and_b32_e32 v143, 0xffff0000, v161
	v_lshlrev_b32_e32 v144, 16, v194
	v_and_b32_e32 v145, 0xffff0000, v194
	v_lshlrev_b32_e32 v146, 16, v195
	v_and_b32_e32 v147, 0xffff0000, v195
	v_lshlrev_b32_e32 v234, 16, v196
	v_and_b32_e32 v235, 0xffff0000, v196
	v_lshlrev_b32_e32 v236, 16, v197
	v_and_b32_e32 v237, 0xffff0000, v197
	v_pk_fma_f32 v[52:53], v[52:53], v[144:145], v[136:137]
	v_pk_fma_f32 v[54:55], v[54:55], v[146:147], v[138:139]
	v_pk_fma_f32 v[48:49], v[48:49], v[234:235], v[140:141]
	v_pk_fma_f32 v[50:51], v[50:51], v[236:237], v[142:143]
	s_nop 0
	v_cvt_pk_bf16_f32 v52, v52, v53
	v_cvt_pk_bf16_f32 v53, v54, v55
	v_cvt_pk_bf16_f32 v54, v48, v49
	v_cvt_pk_bf16_f32 v55, v50, v51
	s_nop 1
	v_permlane16_swap_b32_e32 v52, v54
	v_permlane16_swap_b32_e32 v53, v55
	global_store_dwordx4 v244, v[52:55], s[90:91] offset:256
	s_waitcnt vmcnt(18)
	v_permlane16_swap_b32_e32 v162, v164
	v_permlane16_swap_b32_e32 v163, v165
	v_permlane16_swap_b32_e32 v198, v200
	v_permlane16_swap_b32_e32 v199, v201
	v_lshlrev_b32_e32 v136, 16, v162
	v_and_b32_e32 v137, 0xffff0000, v162
	v_lshlrev_b32_e32 v138, 16, v163
	v_and_b32_e32 v139, 0xffff0000, v163
	v_lshlrev_b32_e32 v140, 16, v164
	v_and_b32_e32 v141, 0xffff0000, v164
	v_lshlrev_b32_e32 v142, 16, v165
	v_and_b32_e32 v143, 0xffff0000, v165
	v_lshlrev_b32_e32 v144, 16, v198
	v_and_b32_e32 v145, 0xffff0000, v198
	v_lshlrev_b32_e32 v146, 16, v199
	v_and_b32_e32 v147, 0xffff0000, v199
	v_lshlrev_b32_e32 v234, 16, v200
	v_and_b32_e32 v235, 0xffff0000, v200
	v_lshlrev_b32_e32 v236, 16, v201
	v_and_b32_e32 v237, 0xffff0000, v201
	v_pk_fma_f32 v[44:45], v[44:45], v[144:145], v[136:137]
	v_pk_fma_f32 v[46:47], v[46:47], v[146:147], v[138:139]
	v_pk_fma_f32 v[40:41], v[40:41], v[234:235], v[140:141]
	v_pk_fma_f32 v[42:43], v[42:43], v[236:237], v[142:143]
	s_nop 0
	v_cvt_pk_bf16_f32 v44, v44, v45
	v_cvt_pk_bf16_f32 v45, v46, v47
	v_cvt_pk_bf16_f32 v46, v40, v41
	v_cvt_pk_bf16_f32 v47, v42, v43
	s_nop 1
	v_permlane16_swap_b32_e32 v44, v46
	v_permlane16_swap_b32_e32 v45, v47
	global_store_dwordx4 v245, v[44:47], s[90:91]
	s_waitcnt vmcnt(16)
	v_permlane16_swap_b32_e32 v166, v168
	v_permlane16_swap_b32_e32 v167, v169
	v_permlane16_swap_b32_e32 v202, v204
	v_permlane16_swap_b32_e32 v203, v205
	v_lshlrev_b32_e32 v136, 16, v166
	v_and_b32_e32 v137, 0xffff0000, v166
	v_lshlrev_b32_e32 v138, 16, v167
	v_and_b32_e32 v139, 0xffff0000, v167
	v_lshlrev_b32_e32 v140, 16, v168
	v_and_b32_e32 v141, 0xffff0000, v168
	v_lshlrev_b32_e32 v142, 16, v169
	v_and_b32_e32 v143, 0xffff0000, v169
	v_lshlrev_b32_e32 v144, 16, v202
	v_and_b32_e32 v145, 0xffff0000, v202
	v_lshlrev_b32_e32 v146, 16, v203
	v_and_b32_e32 v147, 0xffff0000, v203
	v_lshlrev_b32_e32 v234, 16, v204
	v_and_b32_e32 v235, 0xffff0000, v204
	v_lshlrev_b32_e32 v236, 16, v205
	v_and_b32_e32 v237, 0xffff0000, v205
	v_pk_fma_f32 v[36:37], v[36:37], v[144:145], v[136:137]
	v_pk_fma_f32 v[38:39], v[38:39], v[146:147], v[138:139]
	v_pk_fma_f32 v[32:33], v[32:33], v[234:235], v[140:141]
	v_pk_fma_f32 v[34:35], v[34:35], v[236:237], v[142:143]
	s_nop 0
	v_cvt_pk_bf16_f32 v36, v36, v37
	v_cvt_pk_bf16_f32 v37, v38, v39
	v_cvt_pk_bf16_f32 v38, v32, v33
	v_cvt_pk_bf16_f32 v39, v34, v35
	s_nop 1
	v_permlane16_swap_b32_e32 v36, v38
	v_permlane16_swap_b32_e32 v37, v39
	global_store_dwordx4 v245, v[36:39], s[90:91] offset:256
	s_waitcnt vmcnt(14)
	v_permlane16_swap_b32_e32 v170, v172
	v_permlane16_swap_b32_e32 v171, v173
	v_permlane16_swap_b32_e32 v206, v208
	v_permlane16_swap_b32_e32 v207, v209
	v_lshlrev_b32_e32 v136, 16, v170
	v_and_b32_e32 v137, 0xffff0000, v170
	v_lshlrev_b32_e32 v138, 16, v171
	v_and_b32_e32 v139, 0xffff0000, v171
	v_lshlrev_b32_e32 v140, 16, v172
	v_and_b32_e32 v141, 0xffff0000, v172
	v_lshlrev_b32_e32 v142, 16, v173
	v_and_b32_e32 v143, 0xffff0000, v173
	v_lshlrev_b32_e32 v144, 16, v206
	v_and_b32_e32 v145, 0xffff0000, v206
	v_lshlrev_b32_e32 v146, 16, v207
	v_and_b32_e32 v147, 0xffff0000, v207
	v_lshlrev_b32_e32 v234, 16, v208
	v_and_b32_e32 v235, 0xffff0000, v208
	v_lshlrev_b32_e32 v236, 16, v209
	v_and_b32_e32 v237, 0xffff0000, v209
	v_pk_fma_f32 v[28:29], v[28:29], v[144:145], v[136:137]
	v_pk_fma_f32 v[30:31], v[30:31], v[146:147], v[138:139]
	v_pk_fma_f32 v[24:25], v[24:25], v[234:235], v[140:141]
	v_pk_fma_f32 v[26:27], v[26:27], v[236:237], v[142:143]
	s_nop 0
	v_cvt_pk_bf16_f32 v28, v28, v29
	v_cvt_pk_bf16_f32 v29, v30, v31
	v_cvt_pk_bf16_f32 v30, v24, v25
	v_cvt_pk_bf16_f32 v31, v26, v27
	s_nop 1
	v_permlane16_swap_b32_e32 v28, v30
	v_permlane16_swap_b32_e32 v29, v31
	global_store_dwordx4 v246, v[28:31], s[90:91]
	s_waitcnt vmcnt(12)
	v_permlane16_swap_b32_e32 v174, v176
	v_permlane16_swap_b32_e32 v175, v177
	v_permlane16_swap_b32_e32 v210, v212
	v_permlane16_swap_b32_e32 v211, v213
	v_lshlrev_b32_e32 v136, 16, v174
	v_and_b32_e32 v137, 0xffff0000, v174
	v_lshlrev_b32_e32 v138, 16, v175
	v_and_b32_e32 v139, 0xffff0000, v175
	v_lshlrev_b32_e32 v140, 16, v176
	v_and_b32_e32 v141, 0xffff0000, v176
	v_lshlrev_b32_e32 v142, 16, v177
	v_and_b32_e32 v143, 0xffff0000, v177
	v_lshlrev_b32_e32 v144, 16, v210
	v_and_b32_e32 v145, 0xffff0000, v210
	v_lshlrev_b32_e32 v146, 16, v211
	v_and_b32_e32 v147, 0xffff0000, v211
	v_lshlrev_b32_e32 v234, 16, v212
	v_and_b32_e32 v235, 0xffff0000, v212
	v_lshlrev_b32_e32 v236, 16, v213
	v_and_b32_e32 v237, 0xffff0000, v213
	v_pk_fma_f32 v[20:21], v[20:21], v[144:145], v[136:137]
	v_pk_fma_f32 v[22:23], v[22:23], v[146:147], v[138:139]
	v_pk_fma_f32 v[16:17], v[16:17], v[234:235], v[140:141]
	v_pk_fma_f32 v[18:19], v[18:19], v[236:237], v[142:143]
	s_nop 0
	v_cvt_pk_bf16_f32 v20, v20, v21
	v_cvt_pk_bf16_f32 v21, v22, v23
	v_cvt_pk_bf16_f32 v22, v16, v17
	v_cvt_pk_bf16_f32 v23, v18, v19
	s_nop 1
	v_permlane16_swap_b32_e32 v20, v22
	v_permlane16_swap_b32_e32 v21, v23
	global_store_dwordx4 v246, v[20:23], s[90:91] offset:256
	s_waitcnt vmcnt(10)
	v_permlane16_swap_b32_e32 v178, v180
	v_permlane16_swap_b32_e32 v179, v181
	v_permlane16_swap_b32_e32 v214, v216
	v_permlane16_swap_b32_e32 v215, v217
	v_lshlrev_b32_e32 v136, 16, v178
	v_and_b32_e32 v137, 0xffff0000, v178
	v_lshlrev_b32_e32 v138, 16, v179
	v_and_b32_e32 v139, 0xffff0000, v179
	v_lshlrev_b32_e32 v140, 16, v180
	v_and_b32_e32 v141, 0xffff0000, v180
	v_lshlrev_b32_e32 v142, 16, v181
	v_and_b32_e32 v143, 0xffff0000, v181
	v_lshlrev_b32_e32 v144, 16, v214
	v_and_b32_e32 v145, 0xffff0000, v214
	v_lshlrev_b32_e32 v146, 16, v215
	v_and_b32_e32 v147, 0xffff0000, v215
	v_lshlrev_b32_e32 v234, 16, v216
	v_and_b32_e32 v235, 0xffff0000, v216
	v_lshlrev_b32_e32 v236, 16, v217
	v_and_b32_e32 v237, 0xffff0000, v217
	v_pk_fma_f32 v[12:13], v[12:13], v[144:145], v[136:137]
	v_pk_fma_f32 v[14:15], v[14:15], v[146:147], v[138:139]
	v_pk_fma_f32 v[8:9], v[8:9], v[234:235], v[140:141]
	v_pk_fma_f32 v[10:11], v[10:11], v[236:237], v[142:143]
	s_nop 0
	v_cvt_pk_bf16_f32 v12, v12, v13
	v_cvt_pk_bf16_f32 v13, v14, v15
	v_cvt_pk_bf16_f32 v14, v8, v9
	v_cvt_pk_bf16_f32 v15, v10, v11
	s_nop 1
	v_permlane16_swap_b32_e32 v12, v14
	v_permlane16_swap_b32_e32 v13, v15
	global_store_dwordx4 v247, v[12:15], s[90:91]
	s_waitcnt vmcnt(8)
	v_permlane16_swap_b32_e32 v182, v184
	v_permlane16_swap_b32_e32 v183, v185
	v_permlane16_swap_b32_e32 v230, v232
	v_permlane16_swap_b32_e32 v231, v233
	v_lshlrev_b32_e32 v136, 16, v182
	v_and_b32_e32 v137, 0xffff0000, v182
	v_lshlrev_b32_e32 v138, 16, v183
	v_and_b32_e32 v139, 0xffff0000, v183
	v_lshlrev_b32_e32 v140, 16, v184
	v_and_b32_e32 v141, 0xffff0000, v184
	v_lshlrev_b32_e32 v142, 16, v185
	v_and_b32_e32 v143, 0xffff0000, v185
	v_lshlrev_b32_e32 v144, 16, v230
	v_and_b32_e32 v145, 0xffff0000, v230
	v_lshlrev_b32_e32 v146, 16, v231
	v_and_b32_e32 v147, 0xffff0000, v231
	v_lshlrev_b32_e32 v234, 16, v232
	v_and_b32_e32 v235, 0xffff0000, v232
	v_lshlrev_b32_e32 v236, 16, v233
	v_and_b32_e32 v237, 0xffff0000, v233
	v_pk_fma_f32 v[4:5], v[4:5], v[144:145], v[136:137]
	v_pk_fma_f32 v[6:7], v[6:7], v[146:147], v[138:139]
	v_pk_fma_f32 v[0:1], v[0:1], v[234:235], v[140:141]
	v_pk_fma_f32 v[2:3], v[2:3], v[236:237], v[142:143]
	s_nop 0
	v_cvt_pk_bf16_f32 v4, v4, v5
	v_cvt_pk_bf16_f32 v5, v6, v7
	v_cvt_pk_bf16_f32 v6, v0, v1
	v_cvt_pk_bf16_f32 v7, v2, v3
	s_nop 1
	v_permlane16_swap_b32_e32 v4, v6
	v_permlane16_swap_b32_e32 v5, v7
	global_store_dwordx4 v247, v[4:7], s[90:91] offset:256

; #define LAS __attribute__((address_space(3)))
; __device__ __forceinline__ f32x4 ld_bf4(const bf16_t* p) { u32x2 w = *(const u32x2*)p; return (f32x4){__uint_as_float(w.x << 16), __uint_as_float(w.x & 0xffff0000u), __uint_as_float(w.y << 16), __uint_as_float(w.y & 0xffff0000u)}; }
; __device__ __forceinline__ void st_bf4(bf16_t* p, f32x4 v) { u32x2 w; w.x = pk2(v[0], v[1]); w.y = pk2(v[2], v[3]); *(u32x2*)p = w; }
; #define LBAR() do { asm volatile("s_waitcnt lgkmcnt(0)" ::: "memory"); __builtin_amdgcn_s_barrier(); asm volatile("" ::: "memory"); } while (0)
; template <int MODOFF, int STORE  , bool BASE_BF16>
; __device__ __forceinline__ void epi_rows_part1(LAS unsigned char* lds, const f32x4 (&acc)[2][2][4][2], const Unit& u, const float* base, const float* mod, float* outp, float* slots, f32x4 (&xr)[2][16]) {
;     int tid = threadIdx.x; asm volatile("" : "+v"(tid));
;     const int wid = __builtin_amdgcn_readfirstlane(tid >> 6), lane = tid & 63, wr = wid >> 2, wc = wid & 3, fr = lane & 15, fq = lane >> 4;
;     LAS float* T = (LAS float*)lds;
;     const int colg = u.pn * BM + 4 * lane;
;     const f32x4 gt = *(const f32x4*)(mod + ((u.pm * BM) >> 11) * MODW + MODOFF * DM + colg);
; #pragma unroll
;     for (int ai = 0; ai < 2; ++ai) {
;         if (ai) LBAR();
; #pragma unroll
;         for (int m = 0; m < 4; ++m)
; #pragma unroll
;             for (int bj = 0; bj < 2; ++bj)
; #pragma unroll
;                 for (int n = 0; n < 2; ++n) { const int rl = wr * 64 + m * 16 + fr, c4 = (bj * HALF + wc * 32 + n * 16 + 4 * fq) >> 2;
;                     *(LAS f32x4*)(T + rl * 256 + ((c4 ^ (rl & 15)) << 2)) = acc[ai][bj][m][n]; }
;         LBAR();
; #pragma unroll
;         for (int j = 0; j < 16; ++j) { const int rl = wid * 16 + j, row = u.pm * BM + ai * HALF + rl; const size_t o = (size_t)row * DM + colg;
;             const f32x4 v = *(const LAS f32x4*)(T + rl * 256 + ((lane ^ j) << 2));
;             const f32x4 bs = BASE_BF16 ? ld_bf4((const bf16_t*)base + o) : *(const f32x4*)(base + o);
;             const f32x4 x1 = bs + gt * v; xr[ai][j] = x1; if (STORE == 2) st_bf4((bf16_t*)outp + o, x1);
;             const float sq = wave_sum((x1[0] * x1[0] + x1[1] * x1[1]) + (x1[2] * x1[2] + x1[3] * x1[3]));
;             if (lane == 0) __hip_atomic_store((unsigned*)slots + (size_t)row * 8 + u.pn, __float_as_uint(sq), __ATOMIC_RELAXED, __HIP_MEMORY_SCOPE_AGENT); }
.LBB0_1622:
	s_add_u32 s46, s66, 0x50000
	s_addc_u32 s47, s67, 0
	s_lshr_b32 s0, s3, 3
	v_mov_b32_e32 v134, v189
	s_mulk_i32 s0, 0x3000
	s_ashr_i32 s1, s0, 31
	v_readfirstlane_b32 s4, v134
	s_ashr_i32 s9, s4, 6
	s_lshl_b32 s48, s2, 8
	s_lshl_b64 s[0:1], s[0:1], 2
	s_add_u32 s0, s92, s0
	s_addc_u32 s1, s93, s1
	s_lshr_b32 s4, s4, 2
	v_and_b32_e32 v135, 15, v134
	s_and_b32 s4, s4, 0x3fffc0
	v_and_b32_e32 v139, 63, v134
	v_or_b32_e32 v136, s4, v135
	s_lshl_b32 s4, s9, 5
	v_lshrrev_b32_e32 v134, 2, v134
	s_and_b32 s4, s4, 0x60
	v_and_b32_e32 v134, 12, v134
	v_lshlrev_b32_e32 v138, 2, v135
	v_or_b32_e32 v137, s4, v134
	v_lshl_add_u32 v140, v136, 10, 0
	v_bitop3_b32 v134, s4, v138, v134 bitop3:0x36
	s_lshl_b32 s49, s3, 8
	s_ashr_i32 s3, s2, 31
	v_lshl_add_u32 v134, v134, 2, v140
	s_lshl_b32 s8, s9, 4
	s_lshl_b64 s[2:3], s[2:3], 2
	ds_write_b128 v134, v[128:131]
	v_bitop3_b32 v128, v137, v138, 16 bitop3:0x36
	s_add_u32 s6, s46, s2
	v_lshl_add_u32 v135, v128, 2, v140
	s_movk_i32 s2, 0x80
	v_lshl_or_b32 v132, v139, 2, s48
	ds_write_b128 v135, v[124:127]
	v_bitop3_b32 v124, v137, v138, s2 bitop3:0x36
	v_ashrrev_i32_e32 v133, 31, v132
	v_lshl_add_u32 v136, v124, 2, v140
	s_movk_i32 s2, 0x90
	v_lshl_add_u64 v[0:1], v[132:133], 2, s[0:1]
	s_movk_i32 s5, 0x4000
	s_addc_u32 s7, s47, s3
	ds_write_b128 v136, v[120:123]
	v_bitop3_b32 v120, v137, v138, s2 bitop3:0x36
	s_add_i32 s2, s8, s49
	v_add_co_u32_e32 v0, vcc, s5, v0
	s_ashr_i32 s3, s2, 31
	s_nop 0
	v_addc_co_u32_e32 v1, vcc, 0, v1, vcc
	v_lshl_add_u32 v137, v120, 2, v140
	s_lshl_b64 s[4:5], s[2:3], 11
	v_readlane_b32 s12, v254, 1
	global_load_dwordx4 v[0:3], v[0:1], off nt
	ds_write_b128 v137, v[116:119]
	ds_write_b128 v134, v[112:115] offset:16384
	ds_write_b128 v135, v[108:111] offset:16384
	ds_write_b128 v136, v[104:107] offset:16384
	ds_write_b128 v137, v[100:103] offset:16384
	ds_write_b128 v134, v[96:99] offset:32768
	ds_write_b128 v135, v[92:95] offset:32768
	ds_write_b128 v136, v[88:91] offset:32768
	ds_write_b128 v137, v[84:87] offset:32768
	ds_write_b128 v134, v[80:83] offset:49152
	ds_write_b128 v135, v[76:79] offset:49152
	ds_write_b128 v136, v[72:75] offset:49152
	ds_write_b128 v137, v[68:71] offset:49152
	v_lshl_add_u64 v[78:79], s[4:5], 0, v[132:133]
	v_readlane_b32 s13, v254, 2
	s_waitcnt lgkmcnt(0)
	s_barrier
	s_lshl_b32 s4, s9, 14
	v_lshl_add_u64 v[68:69], v[78:79], 2, s[12:13]
	s_mov_b64 s[98:99], 0x2000
	global_load_dwordx4 v[164:167], v[68:69], off nt
	v_lshl_add_u64 v[252:253], v[68:69], 0, s[98:99]
	global_load_dwordx4 v[168:171], v[252:253], off nt
	v_lshl_add_u64 v[252:253], v[252:253], 0, s[98:99]
	global_load_dwordx4 v[172:175], v[252:253], off nt
	v_lshl_add_u64 v[252:253], v[252:253], 0, s[98:99]
	global_load_dwordx4 v[176:179], v[252:253], off nt
	v_lshl_add_u64 v[252:253], v[252:253], 0, s[98:99]
	global_load_dwordx4 v[180:183], v[252:253], off nt
	v_lshl_add_u64 v[252:253], v[252:253], 0, s[98:99]
	global_load_dwordx4 v[184:187], v[252:253], off nt
	v_lshl_add_u64 v[252:253], v[252:253], 0, s[98:99]
	global_load_dwordx4 v[196:199], v[252:253], off nt
	v_lshl_add_u64 v[252:253], v[252:253], 0, s[98:99]
	global_load_dwordx4 v[200:203], v[252:253], off nt
	v_lshl_add_u64 v[252:253], v[252:253], 0, s[98:99]
	global_load_dwordx4 v[204:207], v[252:253], off nt
	v_lshl_add_u64 v[252:253], v[252:253], 0, s[98:99]
	global_load_dwordx4 v[208:211], v[252:253], off nt
	v_lshl_add_u64 v[252:253], v[252:253], 0, s[98:99]
	global_load_dwordx4 v[212:215], v[252:253], off nt
	v_lshl_add_u64 v[252:253], v[252:253], 0, s[98:99]
	global_load_dwordx4 v[216:219], v[252:253], off nt
	v_lshl_add_u64 v[252:253], v[252:253], 0, s[98:99]
	global_load_dwordx4 v[220:223], v[252:253], off nt
	v_lshl_add_u64 v[252:253], v[252:253], 0, s[98:99]
	global_load_dwordx4 v[224:227], v[252:253], off nt
	v_lshl_add_u64 v[252:253], v[252:253], 0, s[98:99]
	global_load_dwordx4 v[228:231], v[252:253], off nt
	v_lshl_add_u64 v[252:253], v[252:253], 0, s[98:99]
	global_load_dwordx4 v[232:235], v[252:253], off nt
	v_lshlrev_b32_e32 v128, 4, v139
	s_add_i32 s4, s4, 0
	v_mbcnt_lo_u32_b32 v68, -1, 0
	v_add_u32_e32 v138, s4, v128
	v_mbcnt_hi_u32_b32 v80, -1, v68
	ds_read_b128 v[74:77], v138
	v_and_b32_e32 v68, 64, v80
	v_xor_b32_e32 v69, 1, v80
	v_add_u32_e32 v81, 64, v68
	v_cmp_lt_i32_e64 s[4:5], v69, v81
	v_cmp_eq_u32_e32 vcc, 0, v139
	v_readlane_b32 s14, v254, 3
	v_cndmask_b32_e64 v68, v80, v69, s[4:5]
	v_lshlrev_b32_e32 v188, 2, v68
	v_readlane_b32 s15, v254, 4
	v_readlane_b32 s16, v254, 5
	v_readlane_b32 s17, v254, 6
	v_readlane_b32 s18, v254, 7
	v_readlane_b32 s19, v254, 8
	v_readlane_b32 s20, v254, 9
	v_readlane_b32 s21, v254, 10
	v_readlane_b32 s22, v254, 11
	v_readlane_b32 s23, v254, 12
	v_readlane_b32 s24, v254, 13
	v_readlane_b32 s25, v254, 14
	v_readlane_b32 s26, v254, 15
	v_readlane_b32 s27, v254, 16
	s_waitcnt vmcnt(15) lgkmcnt(0)
	v_mov_b32_e32 v70, v164
	v_mov_b32_e32 v71, v165
	v_mov_b32_e32 v72, v166
	v_mov_b32_e32 v73, v167
	v_pk_fma_f32 v[68:69], v[2:3], v[76:77], v[72:73]
	v_pk_fma_f32 v[70:71], v[0:1], v[74:75], v[70:71]
	v_mul_f32_e32 v73, v69, v69
	v_mul_f32_e32 v72, v71, v71
	v_fmac_f32_e32 v72, v70, v70
	v_fmac_f32_e32 v73, v68, v68
	v_add_f32_e32 v72, v72, v73
	s_nop 1
	v_mov_b32_dpp v73, v72 quad_perm:[1,0,3,2] row_mask:0xf bank_mask:0xf
	v_xor_b32_e32 v74, 2, v80
	v_cmp_lt_i32_e64 s[4:5], v74, v81
	v_cvt_pk_bf16_f32 v76, v70, v71
	v_cvt_pk_bf16_f32 v77, v68, v69
	v_cndmask_b32_e64 v74, v80, v74, s[4:5]
	v_lshlrev_b32_e32 v190, 2, v74
	s_waitcnt lgkmcnt(0)
	v_add_f32_e32 v72, v72, v73
	s_nop 1
	v_mov_b32_dpp v73, v72 quad_perm:[2,3,0,1] row_mask:0xf bank_mask:0xf
	v_xor_b32_e32 v74, 4, v80
	v_cmp_lt_i32_e64 s[4:5], v74, v81
	s_waitcnt lgkmcnt(0)
	v_add_f32_e32 v72, v72, v73
	v_cndmask_b32_e64 v74, v80, v74, s[4:5]
	v_lshlrev_b32_e32 v191, 2, v74
	s_nop 1
	v_mov_b32_dpp v73, v72 row_ror:12 row_mask:0xf bank_mask:0xf
	v_xor_b32_e32 v74, 8, v80
	v_cmp_lt_i32_e64 s[4:5], v74, v81
	s_waitcnt lgkmcnt(0)
	v_add_f32_e32 v72, v72, v73
	v_cndmask_b32_e64 v74, v80, v74, s[4:5]
	v_lshlrev_b32_e32 v192, 2, v74
	s_nop 1
	v_mov_b32_dpp v73, v72 row_ror:8 row_mask:0xf bank_mask:0xf
	v_xor_b32_e32 v74, 16, v80
	v_cmp_lt_i32_e64 s[4:5], v74, v81
	s_waitcnt lgkmcnt(0)
	v_add_f32_e32 v72, v72, v73
	v_cndmask_b32_e64 v74, v80, v74, s[4:5]
	v_lshlrev_b32_e32 v193, 2, v74
	v_mov_b32_e32 v73, v72
	s_nop 1
	v_permlane16_swap_b32_e32 v72, v73
	v_xor_b32_e32 v74, 32, v80
	v_cmp_lt_i32_e64 s[4:5], v74, v81
	s_waitcnt lgkmcnt(0)
	v_add_f32_e32 v72, v72, v73
	v_cndmask_b32_e64 v74, v80, v74, s[4:5]
	v_lshlrev_b32_e32 v194, 2, v74
	v_mov_b32_e32 v73, v72
	s_nop 1
	v_permlane32_swap_b32_e32 v72, v73
	v_lshl_add_u64 v[74:75], v[78:79], 1, s[64:65]
	global_store_dwordx2 v[74:75], v[76:77], off
	s_and_saveexec_b64 s[4:5], vcc
	s_cbranch_execz .LBB0_1624
	s_lshl_b64 s[2:3], s[2:3], 5
	s_add_u32 s2, s6, s2
	s_addc_u32 s3, s7, s3
	v_mov_b32_e32 v74, 0
	s_waitcnt lgkmcnt(0)
	v_add_f32_e32 v72, v72, v73
	global_store_dword v74, v72, s[2:3] sc1

; #define LAS __attribute__((address_space(3)))
; __device__ __forceinline__ f32x4 ld_bf4(const bf16_t* p) { u32x2 w = *(const u32x2*)p; return (f32x4){__uint_as_float(w.x << 16), __uint_as_float(w.x & 0xffff0000u), __uint_as_float(w.y << 16), __uint_as_float(w.y & 0xffff0000u)}; }
; __device__ __forceinline__ void st_bf4(bf16_t* p, f32x4 v) { u32x2 w; w.x = pk2(v[0], v[1]); w.y = pk2(v[2], v[3]); *(u32x2*)p = w; }
; #define LBAR() do { asm volatile("s_waitcnt lgkmcnt(0)" ::: "memory"); __builtin_amdgcn_s_barrier(); asm volatile("" ::: "memory"); } while (0)
; template <int MODOFF, int STORE  , bool BASE_BF16>
; __device__ __forceinline__ void epi_rows_part1(LAS unsigned char* lds, const f32x4 (&acc)[2][2][4][2], const Unit& u, const float* base, const float* mod, float* outp, float* slots, f32x4 (&xr)[2][16]) {
;     ...
;     for (int ai = 0; ai < 2; ++ai) {
;         if (ai) LBAR();
; #pragma unroll
;         for (int m = 0; m < 4; ++m)
; #pragma unroll
;             for (int bj = 0; bj < 2; ++bj)
; #pragma unroll
;                 for (int n = 0; n < 2; ++n) { const int rl = wr * 64 + m * 16 + fr, c4 = (bj * HALF + wc * 32 + n * 16 + 4 * fq) >> 2;
;                     *(LAS f32x4*)(T + rl * 256 + ((c4 ^ (rl & 15)) << 2)) = acc[ai][bj][m][n]; }
;         LBAR();
; #pragma unroll
;         for (int j = 0; j < 16; ++j) { const int rl = wid * 16 + j, row = u.pm * BM + ai * HALF + rl; const size_t o = (size_t)row * DM + colg;
;             const f32x4 v = *(const LAS f32x4*)(T + rl * 256 + ((lane ^ j) << 2));
;             const f32x4 bs = BASE_BF16 ? ld_bf4((const bf16_t*)base + o) : *(const f32x4*)(base + o);
;             const f32x4 x1 = bs + gt * v; xr[ai][j] = x1; if (STORE == 2) st_bf4((bf16_t*)outp + o, x1);
;             const float sq = wave_sum((x1[0] * x1[0] + x1[1] * x1[1]) + (x1[2] * x1[2] + x1[3] * x1[3]));
;             if (lane == 0) __hip_atomic_store((unsigned*)slots + (size_t)row * 8 + u.pn, __float_as_uint(sq), __ATOMIC_RELAXED, __HIP_MEMORY_SCOPE_AGENT); }
.LBB0_1654:
	s_or_b64 exec, exec, s[4:5]
	s_or_b32 s24, s49, 0x80
	s_add_i32 s2, s8, s24
	s_ashr_i32 s3, s2, 31
	s_lshl_b64 s[4:5], s[2:3], 11
	v_readlane_b32 s72, v254, 1
	s_waitcnt lgkmcnt(0)
	s_barrier
	ds_write_b128 v134, v[64:67]
	ds_write_b128 v135, v[60:63]
	ds_write_b128 v136, v[56:59]
	ds_write_b128 v137, v[52:55]
	ds_write_b128 v134, v[48:51] offset:16384
	ds_write_b128 v135, v[44:47] offset:16384
	ds_write_b128 v136, v[40:43] offset:16384
	ds_write_b128 v137, v[36:39] offset:16384
	ds_write_b128 v134, v[32:35] offset:32768
	ds_write_b128 v135, v[28:31] offset:32768
	ds_write_b128 v136, v[24:27] offset:32768
	ds_write_b128 v137, v[20:23] offset:32768
	ds_write_b128 v134, v[16:19] offset:49152
	ds_write_b128 v135, v[12:15] offset:49152
	ds_write_b128 v136, v[8:11] offset:49152
	ds_write_b128 v137, v[4:7] offset:49152
	v_lshl_add_u64 v[14:15], s[4:5], 0, v[132:133]
	v_readlane_b32 s73, v254, 2
	s_waitcnt lgkmcnt(0)
	s_barrier
	ds_read_b128 v[10:13], v138
	v_lshl_add_u64 v[4:5], v[14:15], 2, s[72:73]
	s_mov_b64 s[98:99], 0x2000
	global_load_dwordx4 v[164:167], v[4:5], off nt
	v_lshl_add_u64 v[252:253], v[4:5], 0, s[98:99]
	global_load_dwordx4 v[168:171], v[252:253], off nt
	v_lshl_add_u64 v[252:253], v[252:253], 0, s[98:99]
	global_load_dwordx4 v[172:175], v[252:253], off nt
	v_lshl_add_u64 v[252:253], v[252:253], 0, s[98:99]
	global_load_dwordx4 v[176:179], v[252:253], off nt
	v_lshl_add_u64 v[252:253], v[252:253], 0, s[98:99]
	global_load_dwordx4 v[180:183], v[252:253], off nt
	v_lshl_add_u64 v[252:253], v[252:253], 0, s[98:99]
	global_load_dwordx4 v[184:187], v[252:253], off nt
	v_lshl_add_u64 v[252:253], v[252:253], 0, s[98:99]
	global_load_dwordx4 v[196:199], v[252:253], off nt
	v_lshl_add_u64 v[252:253], v[252:253], 0, s[98:99]
	global_load_dwordx4 v[200:203], v[252:253], off nt
	v_lshl_add_u64 v[252:253], v[252:253], 0, s[98:99]
	global_load_dwordx4 v[204:207], v[252:253], off nt
	v_lshl_add_u64 v[252:253], v[252:253], 0, s[98:99]
	global_load_dwordx4 v[208:211], v[252:253], off nt
	v_lshl_add_u64 v[252:253], v[252:253], 0, s[98:99]
	global_load_dwordx4 v[212:215], v[252:253], off nt
	v_lshl_add_u64 v[252:253], v[252:253], 0, s[98:99]
	global_load_dwordx4 v[216:219], v[252:253], off nt
	v_lshl_add_u64 v[252:253], v[252:253], 0, s[98:99]
	global_load_dwordx4 v[220:223], v[252:253], off nt
	v_lshl_add_u64 v[252:253], v[252:253], 0, s[98:99]
	global_load_dwordx4 v[224:227], v[252:253], off nt
	v_lshl_add_u64 v[252:253], v[252:253], 0, s[98:99]
	global_load_dwordx4 v[228:231], v[252:253], off nt
	v_lshl_add_u64 v[252:253], v[252:253], 0, s[98:99]
	global_load_dwordx4 v[232:235], v[252:253], off nt
	v_readlane_b32 s74, v254, 3
	v_readlane_b32 s75, v254, 4
	v_readlane_b32 s76, v254, 5
	v_readlane_b32 s77, v254, 6
	v_readlane_b32 s78, v254, 7
	v_readlane_b32 s79, v254, 8
	v_readlane_b32 s80, v254, 9
	v_readlane_b32 s81, v254, 10
	v_readlane_b32 s82, v254, 11
	v_readlane_b32 s83, v254, 12
	v_readlane_b32 s84, v254, 13
	v_readlane_b32 s85, v254, 14
	v_readlane_b32 s86, v254, 15
	v_readlane_b32 s87, v254, 16
	s_waitcnt vmcnt(15) lgkmcnt(0)
	v_mov_b32_e32 v4, v164
	v_mov_b32_e32 v5, v165
	v_mov_b32_e32 v6, v166
	v_mov_b32_e32 v7, v167
	v_pk_fma_f32 v[8:9], v[2:3], v[12:13], v[6:7]
	v_pk_fma_f32 v[10:11], v[0:1], v[10:11], v[4:5]
	v_mul_f32_e32 v5, v9, v9
	v_mul_f32_e32 v4, v11, v11
	v_fmac_f32_e32 v4, v10, v10
	v_fmac_f32_e32 v5, v8, v8
	v_add_f32_e32 v4, v4, v5
	s_nop 1
	v_mov_b32_dpp v5, v4 quad_perm:[1,0,3,2] row_mask:0xf bank_mask:0xf
	v_lshl_add_u64 v[6:7], v[14:15], 1, s[64:65]
	v_cvt_pk_bf16_f32 v12, v10, v11
	v_cvt_pk_bf16_f32 v13, v8, v9
	global_store_dwordx2 v[6:7], v[12:13], off
	s_waitcnt lgkmcnt(0)
	v_add_f32_e32 v4, v4, v5
	s_nop 1
	v_mov_b32_dpp v5, v4 quad_perm:[2,3,0,1] row_mask:0xf bank_mask:0xf
	s_waitcnt lgkmcnt(0)
	v_add_f32_e32 v4, v4, v5
	s_nop 1
	v_mov_b32_dpp v5, v4 row_ror:12 row_mask:0xf bank_mask:0xf
	s_waitcnt lgkmcnt(0)
	v_add_f32_e32 v4, v4, v5
	s_nop 1
	v_mov_b32_dpp v5, v4 row_ror:8 row_mask:0xf bank_mask:0xf
	s_waitcnt lgkmcnt(0)
	v_add_f32_e32 v4, v4, v5
	v_mov_b32_e32 v5, v4
	s_nop 1
	v_permlane16_swap_b32_e32 v4, v5
	s_waitcnt lgkmcnt(0)
	v_add_f32_e32 v4, v4, v5
	v_mov_b32_e32 v5, v4
	s_nop 1
	v_permlane32_swap_b32_e32 v4, v5
	s_and_saveexec_b64 s[4:5], vcc
	s_cbranch_execz .LBB0_1656
	s_lshl_b64 s[2:3], s[2:3], 5
	s_add_u32 s2, s6, s2
	s_addc_u32 s3, s7, s3
	v_mov_b32_e32 v6, 0
	s_waitcnt lgkmcnt(0)
	v_add_f32_e32 v4, v4, v5
	global_store_dword v6, v4, s[2:3] sc1

; #define LAS __attribute__((address_space(3)))
; __device__ __forceinline__ f32x4 ld_bf4(const bf16_t* p) { u32x2 w = *(const u32x2*)p; return (f32x4){__uint_as_float(w.x << 16), __uint_as_float(w.x & 0xffff0000u), __uint_as_float(w.y << 16), __uint_as_float(w.y & 0xffff0000u)}; }
; __device__ __forceinline__ void st_bf4(bf16_t* p, f32x4 v) { u32x2 w; w.x = pk2(v[0], v[1]); w.y = pk2(v[2], v[3]); *(u32x2*)p = w; }
; #define LBAR() do { asm volatile("s_waitcnt lgkmcnt(0)" ::: "memory"); __builtin_amdgcn_s_barrier(); asm volatile("" ::: "memory"); } while (0)
; template <int MODOFF, int STORE  , bool BASE_BF16>
; __device__ __forceinline__ void epi_rows_part1(LAS unsigned char* lds, const f32x4 (&acc)[2][2][4][2], const Unit& u, const float* base, const float* mod, float* outp, float* slots, f32x4 (&xr)[2][16]) {
;     int tid = threadIdx.x; asm volatile("" : "+v"(tid));
;     const int wid = __builtin_amdgcn_readfirstlane(tid >> 6), lane = tid & 63, wr = wid >> 2, wc = wid & 3, fr = lane & 15, fq = lane >> 4;
;     LAS float* T = (LAS float*)lds;
;     const int colg = u.pn * BM + 4 * lane;
;     const f32x4 gt = *(const f32x4*)(mod + ((u.pm * BM) >> 11) * MODW + MODOFF * DM + colg);
; #pragma unroll
;     for (int ai = 0; ai < 2; ++ai) {
;         if (ai) LBAR();
; #pragma unroll
;         for (int m = 0; m < 4; ++m)
; #pragma unroll
;             for (int bj = 0; bj < 2; ++bj)
; #pragma unroll
;                 for (int n = 0; n < 2; ++n) { const int rl = wr * 64 + m * 16 + fr, c4 = (bj * HALF + wc * 32 + n * 16 + 4 * fq) >> 2;
;                     *(LAS f32x4*)(T + rl * 256 + ((c4 ^ (rl & 15)) << 2)) = acc[ai][bj][m][n]; }
;         LBAR();
; #pragma unroll
;         for (int j = 0; j < 16; ++j) { const int rl = wid * 16 + j, row = u.pm * BM + ai * HALF + rl; const size_t o = (size_t)row * DM + colg;
;             const f32x4 v = *(const LAS f32x4*)(T + rl * 256 + ((lane ^ j) << 2));
;             const f32x4 bs = BASE_BF16 ? ld_bf4((const bf16_t*)base + o) : *(const f32x4*)(base + o);
;             const f32x4 x1 = bs + gt * v; xr[ai][j] = x1; if (STORE == 2) st_bf4((bf16_t*)outp + o, x1);
;             const float sq = wave_sum((x1[0] * x1[0] + x1[1] * x1[1]) + (x1[2] * x1[2] + x1[3] * x1[3]));
;             if (lane == 0) __hip_atomic_store((unsigned*)slots + (size_t)row * 8 + u.pn, __float_as_uint(sq), __ATOMIC_RELAXED, __HIP_MEMORY_SCOPE_AGENT); }
.LBB0_1893:
	s_add_u32 s33, s66, 0x90000
	s_addc_u32 s44, s67, 0
	s_lshr_b32 s0, s7, 3
	v_mov_b32_e32 v134, v189
	s_mulk_i32 s0, 0x3000
	s_ashr_i32 s1, s0, 31
	v_readfirstlane_b32 s2, v134
	s_ashr_i32 s9, s2, 6
	v_and_b32_e32 v139, 63, v134
	s_lshl_b32 s45, s6, 8
	s_lshl_b64 s[0:1], s[0:1], 2
	v_lshl_or_b32 v132, v139, 2, s45
	s_add_u32 s0, s92, s0
	s_addc_u32 s1, s93, s1
	v_ashrrev_i32_e32 v133, 31, v132
	v_lshl_add_u64 v[64:65], v[132:133], 2, s[0:1]
	s_mov_b32 s0, 0xa000
	v_add_co_u32_e32 v64, vcc, s0, v64
	s_lshr_b32 s0, s2, 2
	v_and_b32_e32 v135, 15, v134
	s_and_b32 s0, s0, 0x3fffc0
	v_or_b32_e32 v138, s0, v135
	s_lshl_b32 s0, s9, 5
	v_lshrrev_b32_e32 v134, 2, v134
	s_and_b32 s2, s0, 0x60
	v_and_b32_e32 v134, 12, v134
	v_lshlrev_b32_e32 v135, 2, v135
	v_lshl_add_u64 v[136:137], v[132:133], 1, s[64:65]
	v_lshl_add_u32 v138, v138, 10, 0
	v_bitop3_b32 v132, s2, v135, v134 bitop3:0x36
	v_or_b32_e32 v140, s2, v134
	s_lshl_b32 s46, s7, 8
	s_ashr_i32 s7, s6, 31
	v_lshl_add_u32 v132, v132, 2, v138
	s_lshl_b32 s8, s9, 4
	s_lshl_b64 s[0:1], s[6:7], 2
	ds_write_b128 v132, v[128:131]
	v_bitop3_b32 v128, v140, v135, 16 bitop3:0x36
	s_add_u32 s4, s33, s0
	v_lshl_add_u32 v133, v128, 2, v138
	s_movk_i32 s0, 0x80
	ds_write_b128 v133, v[124:127]
	v_bitop3_b32 v124, v140, v135, s0 bitop3:0x36
	v_lshl_add_u32 v134, v124, 2, v138
	s_movk_i32 s0, 0x90
	s_addc_u32 s5, s44, s1
	ds_write_b128 v134, v[120:123]
	v_bitop3_b32 v120, v140, v135, s0 bitop3:0x36
	s_add_i32 s0, s8, s46
	v_addc_co_u32_e32 v65, vcc, 0, v65, vcc
	v_lshl_add_u32 v135, v120, 2, v138
	s_ashr_i32 s1, s0, 31
	global_load_dwordx4 v[64:67], v[64:65], off nt
	ds_write_b128 v135, v[116:119]
	ds_write_b128 v132, v[112:115] offset:16384
	ds_write_b128 v133, v[108:111] offset:16384
	ds_write_b128 v134, v[104:107] offset:16384
	ds_write_b128 v135, v[100:103] offset:16384
	ds_write_b128 v132, v[96:99] offset:32768
	ds_write_b128 v133, v[92:95] offset:32768
	ds_write_b128 v134, v[88:91] offset:32768
	ds_write_b128 v135, v[84:87] offset:32768
	ds_write_b128 v132, v[80:83] offset:49152
	ds_write_b128 v133, v[76:79] offset:49152
	ds_write_b128 v134, v[72:75] offset:49152
	ds_write_b128 v135, v[68:71] offset:49152
	s_lshl_b64 s[2:3], s[0:1], 12
	s_waitcnt lgkmcnt(0)
	s_barrier
	v_lshl_add_u64 v[68:69], v[136:137], 0, s[2:3]
	s_mov_b64 s[98:99], 0x1000
	global_load_dwordx2 v[164:165], v[68:69], off nt
	v_lshl_add_u64 v[252:253], v[68:69], 0, s[98:99]
	global_load_dwordx2 v[168:169], v[252:253], off nt
	v_lshl_add_u64 v[252:253], v[252:253], 0, s[98:99]
	global_load_dwordx2 v[172:173], v[252:253], off nt
	v_lshl_add_u64 v[252:253], v[252:253], 0, s[98:99]
	global_load_dwordx2 v[176:177], v[252:253], off nt
	v_lshl_add_u64 v[252:253], v[252:253], 0, s[98:99]
	global_load_dwordx2 v[180:181], v[252:253], off nt
	v_lshl_add_u64 v[252:253], v[252:253], 0, s[98:99]
	global_load_dwordx2 v[184:185], v[252:253], off nt
	v_lshl_add_u64 v[252:253], v[252:253], 0, s[98:99]
	global_load_dwordx2 v[196:197], v[252:253], off nt
	v_lshl_add_u64 v[252:253], v[252:253], 0, s[98:99]
	global_load_dwordx2 v[200:201], v[252:253], off nt
	v_lshl_add_u64 v[252:253], v[252:253], 0, s[98:99]
	global_load_dwordx2 v[204:205], v[252:253], off nt
	v_lshl_add_u64 v[252:253], v[252:253], 0, s[98:99]
	global_load_dwordx2 v[208:209], v[252:253], off nt
	v_lshl_add_u64 v[252:253], v[252:253], 0, s[98:99]
	global_load_dwordx2 v[212:213], v[252:253], off nt
	v_lshl_add_u64 v[252:253], v[252:253], 0, s[98:99]
	global_load_dwordx2 v[216:217], v[252:253], off nt
	v_lshl_add_u64 v[252:253], v[252:253], 0, s[98:99]
	global_load_dwordx2 v[220:221], v[252:253], off nt
	v_lshl_add_u64 v[252:253], v[252:253], 0, s[98:99]
	global_load_dwordx2 v[224:225], v[252:253], off nt
	v_lshl_add_u64 v[252:253], v[252:253], 0, s[98:99]
	global_load_dwordx2 v[228:229], v[252:253], off nt
	v_lshl_add_u64 v[252:253], v[252:253], 0, s[98:99]
	global_load_dwordx2 v[232:233], v[252:253], off nt
	s_lshl_b32 s2, s9, 14
	v_lshlrev_b32_e32 v124, 4, v139
	s_add_i32 s2, s2, 0
	v_add_u32_e32 v138, s2, v124
	ds_read_b128 v[70:73], v138
	v_cmp_eq_u32_e32 vcc, 0, v139
	s_waitcnt vmcnt(15)
	v_mov_b32_e32 v68, v164
	v_mov_b32_e32 v69, v165
	v_lshlrev_b32_e32 v74, 16, v68
	v_and_b32_e32 v75, 0xffff0000, v68
	v_lshlrev_b32_e32 v68, 16, v69
	v_and_b32_e32 v69, 0xffff0000, v69
	s_waitcnt lgkmcnt(0)
	v_pk_fma_f32 v[68:69], v[66:67], v[72:73], v[68:69]
	v_pk_fma_f32 v[72:73], v[64:65], v[70:71], v[74:75]
	v_mul_f32_e32 v71, v69, v69
	v_mul_f32_e32 v70, v73, v73
	v_fmac_f32_e32 v70, v72, v72
	v_fmac_f32_e32 v71, v68, v68
	v_add_f32_e32 v70, v70, v71
	s_nop 1
	v_mov_b32_dpp v71, v70 quad_perm:[1,0,3,2] row_mask:0xf bank_mask:0xf
	s_waitcnt lgkmcnt(0)
	v_add_f32_e32 v70, v70, v71
	s_nop 1
	v_mov_b32_dpp v71, v70 quad_perm:[2,3,0,1] row_mask:0xf bank_mask:0xf
	s_waitcnt lgkmcnt(0)
	v_add_f32_e32 v70, v70, v71
	s_nop 1
	v_mov_b32_dpp v71, v70 row_ror:12 row_mask:0xf bank_mask:0xf
	s_waitcnt lgkmcnt(0)
	v_add_f32_e32 v70, v70, v71
	s_nop 1
	v_mov_b32_dpp v71, v70 row_ror:8 row_mask:0xf bank_mask:0xf
	s_waitcnt lgkmcnt(0)
	v_add_f32_e32 v70, v70, v71
	v_mov_b32_e32 v71, v70
	s_nop 1
	v_permlane16_swap_b32_e32 v70, v71
	s_waitcnt lgkmcnt(0)
	v_add_f32_e32 v70, v70, v71
	v_mov_b32_e32 v71, v70
	s_nop 1
	v_permlane32_swap_b32_e32 v70, v71
	s_and_saveexec_b64 s[2:3], vcc
	s_cbranch_execz .LBB0_1895
	s_lshl_b64 s[0:1], s[0:1], 5
	s_add_u32 s0, s4, s0
	s_addc_u32 s1, s5, s1
	v_mov_b32_e32 v74, 0
	s_waitcnt lgkmcnt(0)
	v_add_f32_e32 v70, v70, v71
	global_store_dword v74, v70, s[0:1] sc1

; #define LAS __attribute__((address_space(3)))
; __device__ __forceinline__ f32x4 ld_bf4(const bf16_t* p) { u32x2 w = *(const u32x2*)p; return (f32x4){__uint_as_float(w.x << 16), __uint_as_float(w.x & 0xffff0000u), __uint_as_float(w.y << 16), __uint_as_float(w.y & 0xffff0000u)}; }
; __device__ __forceinline__ void st_bf4(bf16_t* p, f32x4 v) { u32x2 w; w.x = pk2(v[0], v[1]); w.y = pk2(v[2], v[3]); *(u32x2*)p = w; }
; #define LBAR() do { asm volatile("s_waitcnt lgkmcnt(0)" ::: "memory"); __builtin_amdgcn_s_barrier(); asm volatile("" ::: "memory"); } while (0)
; template <int MODOFF, int STORE  , bool BASE_BF16>
; __device__ __forceinline__ void epi_rows_part1(LAS unsigned char* lds, const f32x4 (&acc)[2][2][4][2], const Unit& u, const float* base, const float* mod, float* outp, float* slots, f32x4 (&xr)[2][16]) {
;     ...
;                 for (int n = 0; n < 2; ++n) { const int rl = wr * 64 + m * 16 + fr, c4 = (bj * HALF + wc * 32 + n * 16 + 4 * fq) >> 2;
;                     *(LAS f32x4*)(T + rl * 256 + ((c4 ^ (rl & 15)) << 2)) = acc[ai][bj][m][n]; }
;         LBAR();
; #pragma unroll
;         for (int j = 0; j < 16; ++j) { const int rl = wid * 16 + j, row = u.pm * BM + ai * HALF + rl; const size_t o = (size_t)row * DM + colg;
;             const f32x4 v = *(const LAS f32x4*)(T + rl * 256 + ((lane ^ j) << 2));
;             const f32x4 bs = BASE_BF16 ? ld_bf4((const bf16_t*)base + o) : *(const f32x4*)(base + o);
;             const f32x4 x1 = bs + gt * v; xr[ai][j] = x1; if (STORE == 2) st_bf4((bf16_t*)outp + o, x1);
;             const float sq = wave_sum((x1[0] * x1[0] + x1[1] * x1[1]) + (x1[2] * x1[2] + x1[3] * x1[3]));
;             if (lane == 0) __hip_atomic_store((unsigned*)slots + (size_t)row * 8 + u.pn, __float_as_uint(sq), __ATOMIC_RELAXED, __HIP_MEMORY_SCOPE_AGENT); }
.LBB0_1925:
	s_or_b64 exec, exec, s[2:3]
	s_or_b32 s22, s46, 0x80
	s_add_i32 s0, s8, s22
	s_ashr_i32 s1, s0, 31
	s_waitcnt lgkmcnt(0)
	s_barrier
	ds_write_b128 v132, v[60:63]
	ds_write_b128 v133, v[56:59]
	ds_write_b128 v134, v[52:55]
	ds_write_b128 v135, v[48:51]
	ds_write_b128 v132, v[44:47] offset:16384
	ds_write_b128 v133, v[40:43] offset:16384
	ds_write_b128 v134, v[36:39] offset:16384
	ds_write_b128 v135, v[32:35] offset:16384
	ds_write_b128 v132, v[28:31] offset:32768
	ds_write_b128 v133, v[24:27] offset:32768
	ds_write_b128 v134, v[20:23] offset:32768
	ds_write_b128 v135, v[16:19] offset:32768
	ds_write_b128 v132, v[12:15] offset:49152
	ds_write_b128 v133, v[8:11] offset:49152
	ds_write_b128 v134, v[4:7] offset:49152
	ds_write_b128 v135, v[0:3] offset:49152
	s_lshl_b64 s[2:3], s[0:1], 12
	s_waitcnt lgkmcnt(0)
	s_barrier
	v_lshl_add_u64 v[0:1], v[136:137], 0, s[2:3]
	s_mov_b64 s[98:99], 0x1000
	global_load_dwordx2 v[164:165], v[0:1], off nt
	v_lshl_add_u64 v[252:253], v[0:1], 0, s[98:99]
	global_load_dwordx2 v[168:169], v[252:253], off nt
	v_lshl_add_u64 v[252:253], v[252:253], 0, s[98:99]
	global_load_dwordx2 v[172:173], v[252:253], off nt
	v_lshl_add_u64 v[252:253], v[252:253], 0, s[98:99]
	global_load_dwordx2 v[176:177], v[252:253], off nt
	v_lshl_add_u64 v[252:253], v[252:253], 0, s[98:99]
	global_load_dwordx2 v[180:181], v[252:253], off nt
	v_lshl_add_u64 v[252:253], v[252:253], 0, s[98:99]
	global_load_dwordx2 v[184:185], v[252:253], off nt
	v_lshl_add_u64 v[252:253], v[252:253], 0, s[98:99]
	global_load_dwordx2 v[196:197], v[252:253], off nt
	v_lshl_add_u64 v[252:253], v[252:253], 0, s[98:99]
	global_load_dwordx2 v[200:201], v[252:253], off nt
	v_lshl_add_u64 v[252:253], v[252:253], 0, s[98:99]
	global_load_dwordx2 v[204:205], v[252:253], off nt
	v_lshl_add_u64 v[252:253], v[252:253], 0, s[98:99]
	global_load_dwordx2 v[208:209], v[252:253], off nt
	v_lshl_add_u64 v[252:253], v[252:253], 0, s[98:99]
	global_load_dwordx2 v[212:213], v[252:253], off nt
	v_lshl_add_u64 v[252:253], v[252:253], 0, s[98:99]
	global_load_dwordx2 v[216:217], v[252:253], off nt
	v_lshl_add_u64 v[252:253], v[252:253], 0, s[98:99]
	global_load_dwordx2 v[220:221], v[252:253], off nt
	v_lshl_add_u64 v[252:253], v[252:253], 0, s[98:99]
	global_load_dwordx2 v[224:225], v[252:253], off nt
	v_lshl_add_u64 v[252:253], v[252:253], 0, s[98:99]
	global_load_dwordx2 v[228:229], v[252:253], off nt
	v_lshl_add_u64 v[252:253], v[252:253], 0, s[98:99]
	global_load_dwordx2 v[232:233], v[252:253], off nt
	ds_read_b128 v[0:3], v138
	s_waitcnt vmcnt(15)
	v_mov_b32_e32 v4, v164
	v_mov_b32_e32 v5, v165
	v_lshlrev_b32_e32 v6, 16, v4
	v_and_b32_e32 v7, 0xffff0000, v4
	v_lshlrev_b32_e32 v4, 16, v5
	v_and_b32_e32 v5, 0xffff0000, v5
	s_waitcnt lgkmcnt(0)
	v_pk_fma_f32 v[132:133], v[66:67], v[2:3], v[4:5]
	v_pk_fma_f32 v[134:135], v[64:65], v[0:1], v[6:7]
	v_mul_f32_e32 v1, v133, v133
	v_mul_f32_e32 v0, v135, v135
	v_fmac_f32_e32 v0, v134, v134
	v_fmac_f32_e32 v1, v132, v132
	v_add_f32_e32 v0, v0, v1
	s_nop 1
	v_mov_b32_dpp v1, v0 quad_perm:[1,0,3,2] row_mask:0xf bank_mask:0xf
	s_waitcnt lgkmcnt(0)
	v_add_f32_e32 v0, v0, v1
	s_nop 1
	v_mov_b32_dpp v1, v0 quad_perm:[2,3,0,1] row_mask:0xf bank_mask:0xf
	s_waitcnt lgkmcnt(0)
	v_add_f32_e32 v0, v0, v1
	s_nop 1
	v_mov_b32_dpp v1, v0 row_ror:12 row_mask:0xf bank_mask:0xf
	s_waitcnt lgkmcnt(0)
	v_add_f32_e32 v0, v0, v1
	s_nop 1
	v_mov_b32_dpp v1, v0 row_ror:8 row_mask:0xf bank_mask:0xf
	s_waitcnt lgkmcnt(0)
	v_add_f32_e32 v0, v0, v1
	v_mov_b32_e32 v1, v0
	s_nop 1
	v_permlane16_swap_b32_e32 v0, v1
	s_waitcnt lgkmcnt(0)
	v_add_f32_e32 v0, v0, v1
	v_mov_b32_e32 v1, v0
	s_nop 1
	v_permlane32_swap_b32_e32 v0, v1
	s_and_saveexec_b64 s[2:3], vcc
	s_cbranch_execz .LBB0_1927
	s_lshl_b64 s[0:1], s[0:1], 5
	s_add_u32 s0, s4, s0
	s_addc_u32 s1, s5, s1
	v_mov_b32_e32 v2, 0
	s_waitcnt lgkmcnt(0)
	v_add_f32_e32 v0, v0, v1
	global_store_dword v2, v0, s[0:1] sc1
